# GEMM K-loops: the barrier in front of each MFMA block moved behind the block's first 4 MFMAs (it only releases the other half; keeps the matrix pipe busy across the hand-over)
# baseline (speedup 1.0000x reference)
; #define LAS __attribute__((address_space(3)))
; __device__ __forceinline__ unsigned xb_add(unsigned* p, unsigned v) { return __hip_atomic_fetch_add(p, v, __ATOMIC_RELAXED, __HIP_MEMORY_SCOPE_AGENT); }
; __device__ __forceinline__ unsigned xb_xcc_id() { return (unsigned)__builtin_amdgcn_s_getreg((3 << 11) | 20) & 0xFu; }
; __device__ __forceinline__ XcdBarrier xcd_barrier_post(unsigned* bar, volatile LAS unsigned* st) {
;     XcdBarrier b; b.bar = bar; b.x = xb_xcc_id(); b.st = st;
;     if (threadIdx.x == 0) (void)xb_add(&bar[XB_XCNT(b.x)], 1u);
;     return b;
; __global__ void __launch_bounds__(NTHREADS, 2) mk_fwd(Params P) {
;     ...
;     int tid_ = threadIdx.x; asm volatile("" : "+v"(tid_)); const int tid = tid_;
;     volatile LAS unsigned* misc = (volatile LAS unsigned*)(lds + LDS_MAIN);
;     if (tid < 64) misc[tid] = 0u;
;     __syncthreads();
;     unsigned char* ws = P.ws;
;     XcdBarrier bar; bar.bar = (unsigned*)(ws + WS_CTL); bar.x = 0; bar.st = misc;
;     const bool single = (P.ph_hi - P.ph_lo) > 1;
;     if (single) bar = xcd_barrier_post((unsigned*)(ws + WS_CTL), misc);
_Z6mk_fwd6Params:
	s_load_dwordx8 s[4:11], s[0:1], 0x80
	v_mov_b32_e32 v1, v0
	s_waitcnt lgkmcnt(0)
	v_writelane_b32 v251, s4, 0
	s_nop 1
	v_writelane_b32 v251, s5, 1
	v_writelane_b32 v251, s6, 2
	v_writelane_b32 v251, s7, 3
	v_writelane_b32 v251, s8, 4
	v_writelane_b32 v251, s9, 5
	v_writelane_b32 v251, s10, 6
	v_writelane_b32 v251, s11, 7
	s_load_dwordx4 s[88:91], s[0:1], 0xa0
	s_load_dwordx2 s[8:9], s[0:1], 0xb0
	s_waitcnt lgkmcnt(0)
	v_writelane_b32 v251, s8, 8
	s_nop 1
	v_writelane_b32 v251, s9, 9
	v_cmp_gt_i32_e32 vcc, 64, v1
	s_and_saveexec_b64 s[8:9], vcc
	v_lshl_add_u32 v1, v1, 2, 0
	v_add_u32_e32 v1, 0x20800, v1
	v_mov_b32_e32 v2, 0
	ds_write_b32 v1, v2
	s_or_b64 exec, exec, s[8:9]
	s_load_dwordx16 s[40:55], s[0:1], 0x0
	s_load_dwordx16 s[4:19], s[0:1], 0x40
	s_mov_b32 s57, 0
	v_cmp_eq_u32_e32 vcc, 0, v0
	s_waitcnt lgkmcnt(0)
	s_barrier
	v_writelane_b32 v251, s4, 10
	s_nop 1
	v_writelane_b32 v251, s5, 11
	v_writelane_b32 v251, s6, 12
	v_writelane_b32 v251, s7, 13
	v_writelane_b32 v251, s8, 14
	v_writelane_b32 v251, s9, 15
	v_writelane_b32 v251, s10, 16
	v_writelane_b32 v251, s11, 17
	v_writelane_b32 v251, s12, 18
	v_writelane_b32 v251, s13, 19
	v_writelane_b32 v251, s14, 20
	v_writelane_b32 v251, s15, 21
	v_writelane_b32 v251, s16, 22
	v_writelane_b32 v251, s17, 23
	v_writelane_b32 v251, s18, 24
	v_writelane_b32 v251, s19, 25
	v_readfirstlane_b32 s8, v0
	s_nop 3
	s_lshr_b32 s8, s8, 6
	s_cmp_ge_u32 s8, 4
	s_cbranch_scc1 .Lprio_skip
	s_setprio 1
.Lprio_skip:
	s_load_dwordx2 s[8:9], s[0:1], 0xb0
	s_waitcnt lgkmcnt(0)
	s_sub_i32 s3, s9, s8
	s_cmp_gt_i32 s3, 1
	s_cselect_b64 s[4:5], -1, 0
	v_writelane_b32 v251, s4, 26
	s_cmp_lt_i32 s3, 2
	s_mov_b32 s3, 0
	v_writelane_b32 v251, s5, 27
	s_cbranch_scc1 .LBB0_7
	s_getreg_b32 s3, hwreg(HW_REG_XCC_ID, 0, 4)
	s_and_b32 s3, s3, 15
	s_and_saveexec_b64 s[8:9], vcc
	s_cbranch_execz .LBB0_6
	s_mov_b64 s[10:11], exec
	v_mbcnt_lo_u32_b32 v1, s10, 0
	v_mbcnt_hi_u32_b32 v1, s11, v1
	v_cmp_eq_u32_e32 vcc, 0, v1
	s_and_b64 s[12:13], exec, vcc
	s_mov_b64 exec, s[12:13]
	s_cbranch_execz .LBB0_6
	s_lshl_b32 s12, s3, 8
	s_bcnt1_i32_b64 s10, s[10:11]
	v_mov_b32_e32 v1, s12
	v_mov_b32_e32 v2, s10
	global_atomic_add v1, v2, s[90:91] offset:1024

; #define G_STAGE(bufoff, gbase, voff) do { _Pragma("unroll") for (int _i = 0; _i < 2; ++_i) \
;         __builtin_amdgcn_global_load_lds((const unsigned*)((const char*)(gbase) + (voff)[_i]), (LAS unsigned*)(lds + (bufoff) + ldsw + _i * 8192), 16, 0, 0); } while (0)
; #define G_LDA(dst, b, h) do { _Pragma("unroll") for (int m = 0; m < 4; ++m) { const i32x4 _p0 = *(const LAS i32x4*)(lds + G_SA(b, h) + aoff + m * 2048), _p1 = *(const LAS i32x4*)(lds + G_SA(b, h) + aoff + m * 2048 + 1024); \
;         dst[m] = __builtin_shufflevector(_p0, _p1, 0, 1, 2, 3, 4, 5, 6, 7); } } while (0)
; #define G_LDB(dst, b, h) do { _Pragma("unroll") for (int n = 0; n < 2; ++n) { const i32x4 _p0 = *(const LAS i32x4*)(lds + G_SB(b, h) + boff + n * 2048), _p1 = *(const LAS i32x4*)(lds + G_SB(b, h) + boff + n * 2048 + 1024); \
;         dst[n] = __builtin_shufflevector(_p0, _p1, 0, 1, 2, 3, 4, 5, 6, 7); } } while (0)
; #define G_WAIT_V(n) asm volatile("s_waitcnt vmcnt(" #n ")" ::: "memory")
; #define G_WAIT_L(n) asm volatile("s_waitcnt lgkmcnt(" #n ")" ::: "memory")
; #define G_BAR __builtin_amdgcn_s_barrier()
; #define G_SCHED __builtin_amdgcn_sched_barrier(0)
; template <int NS, int MODE  , class Epi>
; __device__ __forceinline__ void gemm_phase(LAS unsigned char* lds, const Gemm g, const StaticOrder& S, const Epi& E) {
;     ...
;             G_LDB(B0, 0, 0); G_LDB(B1, 0, 1); G_SCHED; G_LDA(At, 0, 0); G_STAGE(G_SA(1, 1), a1 + hstep, voffA);
;             G_WAIT_V(8); G_WAIT_L(0); G_BAR; G_MMA(0, 0, At, B0); G_MMA(0, 1, At, B1); G_BAR; G_SCHED;
;             G_LDA(At, 0, 1); G_STAGE(G_SB(0, 0), b2, voffB); G_STAGE(G_SB(0, 1), b2 + hstep, voffB); G_STAGE(G_SA(0, 0), a2, voffA);
;             G_WAIT_V(8); G_WAIT_L(0); G_BAR; G_MMA(1, 0, At, B0); G_MMA(1, 1, At, B1); G_BAR; G_SCHED;
.LBB0_444:
	s_add_i32 s21, 0, 0x10000
	s_add_i32 s30, 0, 0x14000
	v_add_u32_e32 v132, s21, v190
	v_add_u32_e32 v136, s30, v190
	ds_read_b128 v[160:163], v132
	ds_read_b128 v[148:151], v132 offset:1024
	ds_read_b128 v[156:159], v132 offset:2048
	ds_read_b128 v[152:155], v132 offset:3072
	ds_read_b128 v[144:147], v136
	ds_read_b128 v[132:135], v136 offset:1024
	ds_read_b128 v[140:143], v136 offset:2048
	ds_read_b128 v[136:139], v136 offset:3072
	v_lshl_add_u64 v[176:177], v[174:175], 0, s[60:61]
	s_add_i32 m0, s19, 0xc000
	ds_read_b128 v[202:205], v193
	ds_read_b128 v[206:209], v193 offset:1024
	ds_read_b128 v[210:213], v193 offset:2048
	ds_read_b128 v[214:217], v193 offset:3072
	ds_read_b128 v[218:221], v193 offset:4096
	ds_read_b128 v[222:225], v193 offset:5120
	ds_read_b128 v[226:229], v193 offset:6144
	ds_read_b128 v[242:245], v193 offset:7168
	global_load_lds_dwordx4 v[176:177], off
	v_lshl_add_u64 v[176:177], v[186:187], 0, s[60:61]
	s_add_i32 m0, s19, 0xe000
	s_nop 0
	global_load_lds_dwordx4 v[176:177], off
	s_waitcnt vmcnt(8)
	s_waitcnt lgkmcnt(0)
	s_nop 0
	s_waitcnt lgkmcnt(0)
	v_mfma_i32_16x16x64_i8 v[128:131], v[160:163], v[202:205], v[128:131]
	v_mfma_i32_16x16x64_i8 v[120:123], v[156:159], v[202:205], v[120:123]
	v_mfma_i32_16x16x64_i8 v[112:115], v[160:163], v[210:213], v[112:115]
	v_mfma_i32_16x16x64_i8 v[104:107], v[156:159], v[210:213], v[104:107]
	s_barrier
	v_mfma_i32_16x16x64_i8 v[96:99], v[160:163], v[218:221], v[96:99]
	v_mfma_i32_16x16x64_i8 v[88:91], v[156:159], v[218:221], v[88:91]
	v_mfma_i32_16x16x64_i8 v[80:83], v[160:163], v[226:229], v[80:83]
	v_mfma_i32_16x16x64_i8 v[72:75], v[156:159], v[226:229], v[72:75]
	s_nop 0
	v_mfma_i32_16x16x64_i8 v[128:131], v[148:151], v[206:209], v[128:131]
	v_mfma_i32_16x16x64_i8 v[120:123], v[152:155], v[206:209], v[120:123]
	v_mfma_i32_16x16x64_i8 v[112:115], v[148:151], v[214:217], v[112:115]
	v_mfma_i32_16x16x64_i8 v[104:107], v[152:155], v[214:217], v[104:107]
	v_mfma_i32_16x16x64_i8 v[96:99], v[148:151], v[222:225], v[96:99]
	v_mfma_i32_16x16x64_i8 v[88:91], v[152:155], v[222:225], v[88:91]
	v_mfma_i32_16x16x64_i8 v[80:83], v[148:151], v[242:245], v[80:83]
	v_mfma_i32_16x16x64_i8 v[72:75], v[152:155], v[242:245], v[72:75]
	s_nop 0
	s_nop 0
	v_mfma_i32_16x16x64_i8 v[124:127], v[144:147], v[202:205], v[124:127]
	v_mfma_i32_16x16x64_i8 v[116:119], v[140:143], v[202:205], v[116:119]
	v_mfma_i32_16x16x64_i8 v[108:111], v[144:147], v[210:213], v[108:111]
	v_mfma_i32_16x16x64_i8 v[100:103], v[140:143], v[210:213], v[100:103]
	v_mfma_i32_16x16x64_i8 v[92:95], v[144:147], v[218:221], v[92:95]
	v_mfma_i32_16x16x64_i8 v[84:87], v[140:143], v[218:221], v[84:87]
	v_mfma_i32_16x16x64_i8 v[76:79], v[144:147], v[226:229], v[76:79]
	v_mfma_i32_16x16x64_i8 v[68:71], v[140:143], v[226:229], v[68:71]
	s_nop 0
	v_mfma_i32_16x16x64_i8 v[124:127], v[132:135], v[206:209], v[124:127]
	v_mfma_i32_16x16x64_i8 v[116:119], v[136:139], v[206:209], v[116:119]
	v_mfma_i32_16x16x64_i8 v[108:111], v[132:135], v[214:217], v[108:111]
	v_mfma_i32_16x16x64_i8 v[100:103], v[136:139], v[214:217], v[100:103]
	v_mfma_i32_16x16x64_i8 v[92:95], v[132:135], v[222:225], v[92:95]
	v_mfma_i32_16x16x64_i8 v[84:87], v[136:139], v[222:225], v[84:87]
	v_mfma_i32_16x16x64_i8 v[76:79], v[132:135], v[242:245], v[76:79]
	v_mfma_i32_16x16x64_i8 v[68:71], v[136:139], v[242:245], v[68:71]
	s_nop 0
	s_barrier
	s_add_i32 s21, s21, s18
	v_lshl_add_u64 v[176:177], s[68:69], 0, v[2:3]
	s_mov_b32 m0, s21
	ds_read_b128 v[202:205], v193 offset:16384
	ds_read_b128 v[206:209], v193 offset:17408
	ds_read_b128 v[210:213], v193 offset:18432
	ds_read_b128 v[214:217], v193 offset:19456
	ds_read_b128 v[218:221], v193 offset:20480
	ds_read_b128 v[222:225], v193 offset:21504
	ds_read_b128 v[226:229], v193 offset:22528
	ds_read_b128 v[242:245], v193 offset:23552
	global_load_lds_dwordx4 v[176:177], off
	s_add_i32 m0, s21, 0x2000
	s_add_u32 s24, s68, 0x40000
	v_lshl_add_u64 v[176:177], s[68:69], 0, v[164:165]
	s_addc_u32 s25, s69, 0
	s_add_i32 s21, s30, s18
	global_load_lds_dwordx4 v[176:177], off
	v_lshl_add_u64 v[176:177], s[24:25], 0, v[2:3]
	s_mov_b32 m0, s21
	s_nop 0
	global_load_lds_dwordx4 v[176:177], off
	v_lshl_add_u64 v[176:177], s[24:25], 0, v[164:165]
	s_add_i32 m0, s21, 0x2000
	s_nop 0
	global_load_lds_dwordx4 v[176:177], off
	v_lshl_add_u64 v[176:177], s[66:67], 0, v[168:169]
	s_mov_b32 m0, s19
	s_nop 0
	global_load_lds_dwordx4 v[176:177], off
	v_lshl_add_u64 v[176:177], s[66:67], 0, v[166:167]
	s_mov_b32 m0, s29
	s_nop 0
	global_load_lds_dwordx4 v[176:177], off
	s_waitcnt vmcnt(8)
	s_waitcnt lgkmcnt(0)
	s_nop 0
	s_waitcnt lgkmcnt(0)
	v_mfma_i32_16x16x64_i8 v[64:67], v[160:163], v[202:205], v[64:67]
	v_mfma_i32_16x16x64_i8 v[56:59], v[156:159], v[202:205], v[56:59]
	v_mfma_i32_16x16x64_i8 v[48:51], v[160:163], v[210:213], v[48:51]
	v_mfma_i32_16x16x64_i8 v[40:43], v[156:159], v[210:213], v[40:43]
	s_barrier
; #define G_STAGE(bufoff, gbase, voff) do { _Pragma("unroll") for (int _i = 0; _i < 2; ++_i) \
;         __builtin_amdgcn_global_load_lds((const unsigned*)((const char*)(gbase) + (voff)[_i]), (LAS unsigned*)(lds + (bufoff) + ldsw + _i * 8192), 16, 0, 0); } while (0)
; #define G_LDA(dst, b, h) do { _Pragma("unroll") for (int m = 0; m < 4; ++m) { const i32x4 _p0 = *(const LAS i32x4*)(lds + G_SA(b, h) + aoff + m * 2048), _p1 = *(const LAS i32x4*)(lds + G_SA(b, h) + aoff + m * 2048 + 1024); \
;         dst[m] = __builtin_shufflevector(_p0, _p1, 0, 1, 2, 3, 4, 5, 6, 7); } } while (0)
; #define G_LDB(dst, b, h) do { _Pragma("unroll") for (int n = 0; n < 2; ++n) { const i32x4 _p0 = *(const LAS i32x4*)(lds + G_SB(b, h) + boff + n * 2048), _p1 = *(const LAS i32x4*)(lds + G_SB(b, h) + boff + n * 2048 + 1024); \
;         dst[n] = __builtin_shufflevector(_p0, _p1, 0, 1, 2, 3, 4, 5, 6, 7); } } while (0)
; #define G_WAIT_V(n) asm volatile("s_waitcnt vmcnt(" #n ")" ::: "memory")
; #define G_WAIT_L(n) asm volatile("s_waitcnt lgkmcnt(" #n ")" ::: "memory")
; #define G_BAR __builtin_amdgcn_s_barrier()
; #define G_SCHED __builtin_amdgcn_sched_barrier(0)
; template <int NS, int MODE  , class Epi>
; __device__ __forceinline__ void gemm_phase(LAS unsigned char* lds, const Gemm g, const StaticOrder& S, const Epi& E) {
;     ...
;             G_WAIT_V(8); G_WAIT_L(0); G_BAR; G_MMA(1, 0, At, B0); G_MMA(1, 1, At, B1); G_BAR; G_SCHED;
;             G_LDB(B0, 1, 0); G_LDB(B1, 1, 1); G_SCHED; G_LDA(At, 1, 0); G_STAGE(G_SA(0, 1), a2 + hstep, voffA);
;             G_WAIT_V(8); G_WAIT_L(0); G_BAR; G_MMA(0, 0, At, B0); G_MMA(0, 1, At, B1); G_BAR; G_SCHED;
	v_mfma_i32_16x16x64_i8 v[32:35], v[160:163], v[218:221], v[32:35]
	v_mfma_i32_16x16x64_i8 v[24:27], v[156:159], v[218:221], v[24:27]
	v_mfma_i32_16x16x64_i8 v[16:19], v[160:163], v[226:229], v[16:19]
	v_mfma_i32_16x16x64_i8 v[8:11], v[156:159], v[226:229], v[8:11]
	s_nop 0
	v_mfma_i32_16x16x64_i8 v[64:67], v[148:151], v[206:209], v[64:67]
	v_mfma_i32_16x16x64_i8 v[56:59], v[152:155], v[206:209], v[56:59]
	v_mfma_i32_16x16x64_i8 v[48:51], v[148:151], v[214:217], v[48:51]
	v_mfma_i32_16x16x64_i8 v[40:43], v[152:155], v[214:217], v[40:43]
	v_mfma_i32_16x16x64_i8 v[32:35], v[148:151], v[222:225], v[32:35]
	v_mfma_i32_16x16x64_i8 v[24:27], v[152:155], v[222:225], v[24:27]
	v_mfma_i32_16x16x64_i8 v[16:19], v[148:151], v[242:245], v[16:19]
	v_mfma_i32_16x16x64_i8 v[8:11], v[152:155], v[242:245], v[8:11]
	s_nop 0
	s_nop 0
	v_mfma_i32_16x16x64_i8 v[60:63], v[144:147], v[202:205], v[60:63]
	v_mfma_i32_16x16x64_i8 v[52:55], v[140:143], v[202:205], v[52:55]
	v_mfma_i32_16x16x64_i8 v[44:47], v[144:147], v[210:213], v[44:47]
	v_mfma_i32_16x16x64_i8 v[36:39], v[140:143], v[210:213], v[36:39]
	v_mfma_i32_16x16x64_i8 v[28:31], v[144:147], v[218:221], v[28:31]
	v_mfma_i32_16x16x64_i8 v[20:23], v[140:143], v[218:221], v[20:23]
	v_mfma_i32_16x16x64_i8 v[12:15], v[144:147], v[226:229], v[12:15]
	v_mfma_i32_16x16x64_i8 v[4:7], v[140:143], v[226:229], v[4:7]
	s_nop 0
	v_mfma_i32_16x16x64_i8 v[60:63], v[132:135], v[206:209], v[60:63]
	v_mfma_i32_16x16x64_i8 v[52:55], v[136:139], v[206:209], v[52:55]
	v_mfma_i32_16x16x64_i8 v[44:47], v[132:135], v[214:217], v[44:47]
	v_mfma_i32_16x16x64_i8 v[36:39], v[136:139], v[214:217], v[36:39]
	v_mfma_i32_16x16x64_i8 v[28:31], v[132:135], v[222:225], v[28:31]
	v_mfma_i32_16x16x64_i8 v[20:23], v[136:139], v[222:225], v[20:23]
	v_mfma_i32_16x16x64_i8 v[12:15], v[132:135], v[242:245], v[12:15]
	v_mfma_i32_16x16x64_i8 v[4:7], v[136:139], v[242:245], v[4:7]
	s_nop 0
	s_barrier
	s_add_i32 s21, 0, 0x18000
	s_add_i32 s30, 0, 0x1c000
	v_add_u32_e32 v144, s21, v190
	v_add_u32_e32 v160, s30, v190
	ds_read_b128 v[132:135], v144
	ds_read_b128 v[136:139], v144 offset:1024
	ds_read_b128 v[140:143], v144 offset:2048
	ds_read_b128 v[144:147], v144 offset:3072
	ds_read_b128 v[148:151], v160
	ds_read_b128 v[152:155], v160 offset:1024
	ds_read_b128 v[156:159], v160 offset:2048
	ds_read_b128 v[160:163], v160 offset:3072
	s_add_u32 s24, s66, 0x40000
	s_addc_u32 s25, s67, 0
	s_mov_b32 m0, s56
	v_lshl_add_u64 v[176:177], s[24:25], 0, v[168:169]
	ds_read_b128 v[202:205], v193 offset:32768
	ds_read_b128 v[206:209], v193 offset:33792
	ds_read_b128 v[210:213], v193 offset:34816
	ds_read_b128 v[214:217], v193 offset:35840
	ds_read_b128 v[218:221], v193 offset:36864
	ds_read_b128 v[222:225], v193 offset:37888
	ds_read_b128 v[226:229], v193 offset:38912
	ds_read_b128 v[242:245], v193 offset:39936
	global_load_lds_dwordx4 v[176:177], off
	v_lshl_add_u64 v[176:177], s[24:25], 0, v[166:167]
	s_mov_b32 m0, s70
	s_nop 0
	global_load_lds_dwordx4 v[176:177], off
	s_waitcnt vmcnt(8)
	s_waitcnt lgkmcnt(0)
	s_nop 0
	s_waitcnt lgkmcnt(0)
	v_mfma_i32_16x16x64_i8 v[128:131], v[132:135], v[202:205], v[128:131]
	v_mfma_i32_16x16x64_i8 v[120:123], v[140:143], v[202:205], v[120:123]
	v_mfma_i32_16x16x64_i8 v[112:115], v[132:135], v[210:213], v[112:115]
	v_mfma_i32_16x16x64_i8 v[104:107], v[140:143], v[210:213], v[104:107]
	s_barrier
	v_mfma_i32_16x16x64_i8 v[96:99], v[132:135], v[218:221], v[96:99]
	v_mfma_i32_16x16x64_i8 v[88:91], v[140:143], v[218:221], v[88:91]
	v_mfma_i32_16x16x64_i8 v[80:83], v[132:135], v[226:229], v[80:83]
	v_mfma_i32_16x16x64_i8 v[72:75], v[140:143], v[226:229], v[72:75]
	s_nop 0
	v_mfma_i32_16x16x64_i8 v[128:131], v[136:139], v[206:209], v[128:131]
	v_mfma_i32_16x16x64_i8 v[120:123], v[144:147], v[206:209], v[120:123]
	v_mfma_i32_16x16x64_i8 v[112:115], v[136:139], v[214:217], v[112:115]
	v_mfma_i32_16x16x64_i8 v[104:107], v[144:147], v[214:217], v[104:107]
	v_mfma_i32_16x16x64_i8 v[96:99], v[136:139], v[222:225], v[96:99]
	v_mfma_i32_16x16x64_i8 v[88:91], v[144:147], v[222:225], v[88:91]
	v_mfma_i32_16x16x64_i8 v[80:83], v[136:139], v[242:245], v[80:83]
	v_mfma_i32_16x16x64_i8 v[72:75], v[144:147], v[242:245], v[72:75]
	s_nop 0
	s_nop 0
	v_mfma_i32_16x16x64_i8 v[124:127], v[148:151], v[202:205], v[124:127]
	v_mfma_i32_16x16x64_i8 v[116:119], v[156:159], v[202:205], v[116:119]
	v_mfma_i32_16x16x64_i8 v[108:111], v[148:151], v[210:213], v[108:111]
	v_mfma_i32_16x16x64_i8 v[100:103], v[156:159], v[210:213], v[100:103]
	v_mfma_i32_16x16x64_i8 v[92:95], v[148:151], v[218:221], v[92:95]
	v_mfma_i32_16x16x64_i8 v[84:87], v[156:159], v[218:221], v[84:87]
	v_mfma_i32_16x16x64_i8 v[76:79], v[148:151], v[226:229], v[76:79]
	v_mfma_i32_16x16x64_i8 v[68:71], v[156:159], v[226:229], v[68:71]
	s_nop 0
	v_mfma_i32_16x16x64_i8 v[124:127], v[152:155], v[206:209], v[124:127]
	v_mfma_i32_16x16x64_i8 v[116:119], v[160:163], v[206:209], v[116:119]
	v_mfma_i32_16x16x64_i8 v[108:111], v[152:155], v[214:217], v[108:111]
	v_mfma_i32_16x16x64_i8 v[100:103], v[160:163], v[214:217], v[100:103]
	v_mfma_i32_16x16x64_i8 v[92:95], v[152:155], v[222:225], v[92:95]
	v_mfma_i32_16x16x64_i8 v[84:87], v[160:163], v[222:225], v[84:87]
	v_mfma_i32_16x16x64_i8 v[76:79], v[152:155], v[242:245], v[76:79]
	v_mfma_i32_16x16x64_i8 v[68:71], v[160:163], v[242:245], v[68:71]
	s_nop 0
	s_barrier
; #define G_STAGE(bufoff, gbase, voff) do { _Pragma("unroll") for (int _i = 0; _i < 2; ++_i) \
;         __builtin_amdgcn_global_load_lds((const unsigned*)((const char*)(gbase) + (voff)[_i]), (LAS unsigned*)(lds + (bufoff) + ldsw + _i * 8192), 16, 0, 0); } while (0)
; #define G_LDA(dst, b, h) do { _Pragma("unroll") for (int m = 0; m < 4; ++m) { const i32x4 _p0 = *(const LAS i32x4*)(lds + G_SA(b, h) + aoff + m * 2048), _p1 = *(const LAS i32x4*)(lds + G_SA(b, h) + aoff + m * 2048 + 1024); \
;         dst[m] = __builtin_shufflevector(_p0, _p1, 0, 1, 2, 3, 4, 5, 6, 7); } } while (0)
; #define G_WAIT_V(n) asm volatile("s_waitcnt vmcnt(" #n ")" ::: "memory")
; #define G_WAIT_L(n) asm volatile("s_waitcnt lgkmcnt(" #n ")" ::: "memory")
; #define G_BAR __builtin_amdgcn_s_barrier()
; #define G_SCHED __builtin_amdgcn_sched_barrier(0)
; template <int NS, int MODE  , class Epi>
; __device__ __forceinline__ void gemm_phase(LAS unsigned char* lds, const Gemm g, const StaticOrder& S, const Epi& E) {
;     ...
;         for (int t = 0; t < NT; t += 2) {
;     ...
;             G_LDA(At, 1, 1); G_STAGE(G_SB(1, 0), b3, voffB); G_STAGE(G_SB(1, 1), b3 + hstep, voffB); G_STAGE(G_SA(1, 0), a3, voffA);
;             G_WAIT_V(8); G_WAIT_L(0); G_BAR; G_MMA(1, 0, At, B0); G_MMA(1, 1, At, B1); G_BAR; G_SCHED;
	s_add_i32 s21, s21, s18
	v_lshl_add_u64 v[176:177], s[64:65], 0, v[2:3]
	s_mov_b32 m0, s21
	ds_read_b128 v[202:205], v193 offset:49152
	ds_read_b128 v[206:209], v193 offset:50176
	ds_read_b128 v[210:213], v193 offset:51200
	ds_read_b128 v[214:217], v193 offset:52224
	ds_read_b128 v[218:221], v193 offset:53248
	ds_read_b128 v[222:225], v193 offset:54272
	ds_read_b128 v[226:229], v193 offset:55296
	ds_read_b128 v[242:245], v193 offset:56320
	global_load_lds_dwordx4 v[176:177], off
	s_add_i32 m0, s21, 0x2000
	s_add_u32 s24, s64, 0x40000
	v_lshl_add_u64 v[176:177], s[64:65], 0, v[164:165]
	s_addc_u32 s25, s65, 0
	s_add_i32 s21, s30, s18
	global_load_lds_dwordx4 v[176:177], off
	v_lshl_add_u64 v[176:177], s[24:25], 0, v[2:3]
	s_mov_b32 m0, s21
	s_nop 0
	global_load_lds_dwordx4 v[176:177], off
	v_lshl_add_u64 v[176:177], s[24:25], 0, v[164:165]
	s_add_i32 m0, s21, 0x2000
	s_nop 0
	global_load_lds_dwordx4 v[176:177], off
	v_lshl_add_u64 v[176:177], s[62:63], 0, v[168:169]
	s_mov_b32 m0, s71
	s_nop 0
	global_load_lds_dwordx4 v[176:177], off
	v_lshl_add_u64 v[176:177], s[62:63], 0, v[166:167]
	s_mov_b32 m0, s72
	s_nop 0
	global_load_lds_dwordx4 v[176:177], off
	s_waitcnt vmcnt(8)
	s_waitcnt lgkmcnt(0)
	s_nop 0
	s_waitcnt lgkmcnt(0)
	v_mfma_i32_16x16x64_i8 v[64:67], v[132:135], v[202:205], v[64:67]
	v_mfma_i32_16x16x64_i8 v[56:59], v[140:143], v[202:205], v[56:59]
	v_mfma_i32_16x16x64_i8 v[48:51], v[132:135], v[210:213], v[48:51]
	v_mfma_i32_16x16x64_i8 v[40:43], v[140:143], v[210:213], v[40:43]
	s_barrier
	v_mfma_i32_16x16x64_i8 v[32:35], v[132:135], v[218:221], v[32:35]
	v_mfma_i32_16x16x64_i8 v[24:27], v[140:143], v[218:221], v[24:27]
	v_mfma_i32_16x16x64_i8 v[16:19], v[132:135], v[226:229], v[16:19]
	v_mfma_i32_16x16x64_i8 v[8:11], v[140:143], v[226:229], v[8:11]
	s_nop 0
	v_mfma_i32_16x16x64_i8 v[64:67], v[136:139], v[206:209], v[64:67]
	v_mfma_i32_16x16x64_i8 v[56:59], v[144:147], v[206:209], v[56:59]
	v_mfma_i32_16x16x64_i8 v[48:51], v[136:139], v[214:217], v[48:51]
	v_mfma_i32_16x16x64_i8 v[40:43], v[144:147], v[214:217], v[40:43]
	v_mfma_i32_16x16x64_i8 v[32:35], v[136:139], v[222:225], v[32:35]
	v_mfma_i32_16x16x64_i8 v[24:27], v[144:147], v[222:225], v[24:27]
	v_mfma_i32_16x16x64_i8 v[16:19], v[136:139], v[242:245], v[16:19]
	v_mfma_i32_16x16x64_i8 v[8:11], v[144:147], v[242:245], v[8:11]
	s_nop 0
	s_nop 0
	v_mfma_i32_16x16x64_i8 v[60:63], v[148:151], v[202:205], v[60:63]
	v_mfma_i32_16x16x64_i8 v[52:55], v[156:159], v[202:205], v[52:55]
	v_mfma_i32_16x16x64_i8 v[44:47], v[148:151], v[210:213], v[44:47]
	v_mfma_i32_16x16x64_i8 v[36:39], v[156:159], v[210:213], v[36:39]
	v_mfma_i32_16x16x64_i8 v[28:31], v[148:151], v[218:221], v[28:31]
	v_mfma_i32_16x16x64_i8 v[20:23], v[156:159], v[218:221], v[20:23]
	v_mfma_i32_16x16x64_i8 v[12:15], v[148:151], v[226:229], v[12:15]
	v_mfma_i32_16x16x64_i8 v[4:7], v[156:159], v[226:229], v[4:7]
	s_nop 0
	v_mfma_i32_16x16x64_i8 v[60:63], v[152:155], v[206:209], v[60:63]
	v_mfma_i32_16x16x64_i8 v[52:55], v[160:163], v[206:209], v[52:55]
	v_mfma_i32_16x16x64_i8 v[44:47], v[152:155], v[214:217], v[44:47]
	v_mfma_i32_16x16x64_i8 v[36:39], v[160:163], v[214:217], v[36:39]
	v_mfma_i32_16x16x64_i8 v[28:31], v[152:155], v[222:225], v[28:31]
	v_mfma_i32_16x16x64_i8 v[20:23], v[160:163], v[222:225], v[20:23]
	v_mfma_i32_16x16x64_i8 v[12:15], v[152:155], v[242:245], v[12:15]
	v_mfma_i32_16x16x64_i8 v[4:7], v[160:163], v[242:245], v[4:7]
	s_nop 0
	s_barrier
	s_add_i32 s13, s13, 2
	s_add_u32 s60, s60, 0x100
	s_addc_u32 s61, s61, 0
	s_cmp_gt_u32 s13, 13
	s_cbranch_scc1 .LBB0_447

; #define G_STAGE(bufoff, gbase, voff) do { _Pragma("unroll") for (int _i = 0; _i < 2; ++_i) \
;         __builtin_amdgcn_global_load_lds((const unsigned*)((const char*)(gbase) + (voff)[_i]), (LAS unsigned*)(lds + (bufoff) + ldsw + _i * 8192), 16, 0, 0); } while (0)
; #define G_LDA(dst, b, h) do { _Pragma("unroll") for (int m = 0; m < 4; ++m) { const i32x4 _p0 = *(const LAS i32x4*)(lds + G_SA(b, h) + aoff + m * 2048), _p1 = *(const LAS i32x4*)(lds + G_SA(b, h) + aoff + m * 2048 + 1024); \
;         dst[m] = __builtin_shufflevector(_p0, _p1, 0, 1, 2, 3, 4, 5, 6, 7); } } while (0)
; #define G_LDB(dst, b, h) do { _Pragma("unroll") for (int n = 0; n < 2; ++n) { const i32x4 _p0 = *(const LAS i32x4*)(lds + G_SB(b, h) + boff + n * 2048), _p1 = *(const LAS i32x4*)(lds + G_SB(b, h) + boff + n * 2048 + 1024); \
;         dst[n] = __builtin_shufflevector(_p0, _p1, 0, 1, 2, 3, 4, 5, 6, 7); } } while (0)
; #define G_WAIT_V(n) asm volatile("s_waitcnt vmcnt(" #n ")" ::: "memory")
; #define G_WAIT_L(n) asm volatile("s_waitcnt lgkmcnt(" #n ")" ::: "memory")
; #define G_BAR __builtin_amdgcn_s_barrier()
; #define G_SCHED __builtin_amdgcn_sched_barrier(0)
; template <int NS, int MODE  , class Epi>
; __device__ __forceinline__ void gemm_phase(LAS unsigned char* lds, const Gemm g, const StaticOrder& S, const Epi& E) {
;     ...
;             G_LDB(B0, 0, 0); G_LDB(B1, 0, 1); G_SCHED; G_LDA(At, 0, 0); G_STAGE(G_SA(1, 1), a1 + hstep, voffA);
;             G_WAIT_V(8); G_WAIT_L(0); G_BAR; G_MMA(0, 0, At, B0); G_MMA(0, 1, At, B1); G_BAR; G_SCHED;
;             G_LDA(At, 0, 1); G_STAGE(G_SB(0, 0), b2, voffB); G_STAGE(G_SB(0, 1), b2 + hstep, voffB); G_STAGE(G_SA(0, 0), a2, voffA);
;             G_WAIT_V(8); G_WAIT_L(0); G_BAR; G_MMA(1, 0, At, B0); G_MMA(1, 1, At, B1); G_BAR; G_SCHED;
;             G_LDB(B0, 1, 0); G_LDB(B1, 1, 1); G_SCHED; G_LDA(At, 1, 0); G_STAGE(G_SA(0, 1), a2 + hstep, voffA);
;             G_WAIT_V(8); G_WAIT_L(0); G_BAR; G_MMA(0, 0, At, B0); G_MMA(0, 1, At, B1); G_BAR; G_SCHED;
.LBB0_525:
	s_add_i32 s25, 0, 0x10000
	s_add_i32 s30, 0, 0x14000
	v_add_u32_e32 v4, s25, v244
	v_add_u32_e32 v16, s30, v244
	ds_read_b128 v[20:23], v4
	ds_read_b128 v[24:27], v4 offset:1024
	ds_read_b128 v[28:31], v4 offset:2048
	ds_read_b128 v[32:35], v4 offset:3072
	ds_read_b128 v[4:7], v16
	ds_read_b128 v[8:11], v16 offset:1024
	ds_read_b128 v[12:15], v16 offset:2048
	ds_read_b128 v[16:19], v16 offset:3072
	v_lshl_add_u64 v[176:177], v[164:165], 0, s[46:47]
	s_add_i32 m0, s19, 0xc000
	ds_read_b128 v[168:171], v246
	ds_read_b128 v[172:175], v246 offset:1024
	ds_read_b128 v[196:199], v246 offset:2048
	ds_read_b128 v[200:203], v246 offset:3072
	ds_read_b128 v[204:207], v246 offset:4096
	ds_read_b128 v[208:211], v246 offset:5120
	ds_read_b128 v[212:215], v246 offset:6144
	ds_read_b128 v[216:219], v246 offset:7168
	global_load_lds_dwordx4 v[176:177], off
	v_lshl_add_u64 v[176:177], v[166:167], 0, s[46:47]
	s_add_i32 m0, s19, 0xe000
	s_nop 0
	global_load_lds_dwordx4 v[176:177], off
	s_waitcnt vmcnt(8)
	s_waitcnt lgkmcnt(0)
	s_nop 0
	s_waitcnt lgkmcnt(0)
	v_mfma_scale_f32_16x16x128_f8f6f4 v[160:163], v[20:27], v[168:175], v[160:163], v242, v242 op_sel_hi:[0,0,0]
	v_mfma_scale_f32_16x16x128_f8f6f4 v[156:159], v[28:35], v[168:175], v[156:159], v242, v242 op_sel_hi:[0,0,0]
	v_mfma_scale_f32_16x16x128_f8f6f4 v[148:151], v[20:27], v[196:203], v[148:151], v242, v242 op_sel_hi:[0,0,0]
	v_mfma_scale_f32_16x16x128_f8f6f4 v[144:147], v[28:35], v[196:203], v[144:147], v242, v242 op_sel_hi:[0,0,0]
	s_barrier
	v_mfma_scale_f32_16x16x128_f8f6f4 v[128:131], v[20:27], v[204:211], v[128:131], v242, v242 op_sel_hi:[0,0,0]
	v_mfma_scale_f32_16x16x128_f8f6f4 v[124:127], v[28:35], v[204:211], v[124:127], v242, v242 op_sel_hi:[0,0,0]
	v_mfma_scale_f32_16x16x128_f8f6f4 v[120:123], v[20:27], v[212:219], v[120:123], v242, v242 op_sel_hi:[0,0,0]
	v_mfma_scale_f32_16x16x128_f8f6f4 v[116:119], v[28:35], v[212:219], v[116:119], v242, v242 op_sel_hi:[0,0,0]
	s_nop 0
	s_nop 0
	v_mfma_scale_f32_16x16x128_f8f6f4 v[152:155], v[4:11], v[168:175], v[152:155], v242, v242 op_sel_hi:[0,0,0]
	v_mfma_scale_f32_16x16x128_f8f6f4 v[140:143], v[12:19], v[168:175], v[140:143], v242, v242 op_sel_hi:[0,0,0]
	v_mfma_scale_f32_16x16x128_f8f6f4 v[136:139], v[4:11], v[196:203], v[136:139], v242, v242 op_sel_hi:[0,0,0]
	v_mfma_scale_f32_16x16x128_f8f6f4 v[132:135], v[12:19], v[196:203], v[132:135], v242, v242 op_sel_hi:[0,0,0]
	v_mfma_scale_f32_16x16x128_f8f6f4 v[112:115], v[4:11], v[204:211], v[112:115], v242, v242 op_sel_hi:[0,0,0]
	v_mfma_scale_f32_16x16x128_f8f6f4 v[108:111], v[12:19], v[204:211], v[108:111], v242, v242 op_sel_hi:[0,0,0]
	v_mfma_scale_f32_16x16x128_f8f6f4 v[104:107], v[4:11], v[212:219], v[104:107], v242, v242 op_sel_hi:[0,0,0]
	v_mfma_scale_f32_16x16x128_f8f6f4 v[100:103], v[12:19], v[212:219], v[100:103], v242, v242 op_sel_hi:[0,0,0]
	s_nop 0
	s_barrier
	s_add_i32 s25, s25, s18
	v_lshl_add_u64 v[176:177], s[60:61], 0, v[2:3]
	s_mov_b32 m0, s25
	ds_read_b128 v[168:171], v246 offset:16384
	ds_read_b128 v[172:175], v246 offset:17408
	ds_read_b128 v[196:199], v246 offset:18432
	ds_read_b128 v[200:203], v246 offset:19456
	ds_read_b128 v[204:207], v246 offset:20480
	ds_read_b128 v[208:211], v246 offset:21504
	ds_read_b128 v[212:215], v246 offset:22528
	ds_read_b128 v[216:219], v246 offset:23552
	global_load_lds_dwordx4 v[176:177], off
	s_add_i32 m0, s25, 0x2000
	v_lshl_add_u64 v[176:177], s[60:61], 0, v[186:187]
	s_add_u32 s60, s60, 0xb0000
	s_addc_u32 s61, s61, 0
	s_add_i32 s25, s30, s18
	global_load_lds_dwordx4 v[176:177], off
	v_lshl_add_u64 v[176:177], s[60:61], 0, v[2:3]
	s_mov_b32 m0, s25
	s_nop 0
	global_load_lds_dwordx4 v[176:177], off
	v_lshl_add_u64 v[176:177], s[60:61], 0, v[186:187]
	s_add_i32 m0, s25, 0x2000
	s_nop 0
	global_load_lds_dwordx4 v[176:177], off
	v_lshl_add_u64 v[176:177], s[58:59], 0, v[190:191]
	s_mov_b32 m0, s19
	s_nop 0
	global_load_lds_dwordx4 v[176:177], off
	v_lshl_add_u64 v[176:177], s[58:59], 0, v[188:189]
	s_mov_b32 m0, s29
	s_nop 0
	global_load_lds_dwordx4 v[176:177], off
	s_waitcnt vmcnt(8)
	s_waitcnt lgkmcnt(0)
	s_nop 0
	s_waitcnt lgkmcnt(0)
	v_mfma_scale_f32_16x16x128_f8f6f4 v[96:99], v[20:27], v[168:175], v[96:99], v242, v242 op_sel_hi:[0,0,0]
	v_mfma_scale_f32_16x16x128_f8f6f4 v[92:95], v[28:35], v[168:175], v[92:95], v242, v242 op_sel_hi:[0,0,0]
	v_mfma_scale_f32_16x16x128_f8f6f4 v[88:91], v[20:27], v[196:203], v[88:91], v242, v242 op_sel_hi:[0,0,0]
	v_mfma_scale_f32_16x16x128_f8f6f4 v[84:87], v[28:35], v[196:203], v[84:87], v242, v242 op_sel_hi:[0,0,0]
	s_barrier
	v_mfma_scale_f32_16x16x128_f8f6f4 v[64:67], v[20:27], v[204:211], v[64:67], v242, v242 op_sel_hi:[0,0,0]
	v_mfma_scale_f32_16x16x128_f8f6f4 v[60:63], v[28:35], v[204:211], v[60:63], v242, v242 op_sel_hi:[0,0,0]
	v_mfma_scale_f32_16x16x128_f8f6f4 v[56:59], v[20:27], v[212:219], v[56:59], v242, v242 op_sel_hi:[0,0,0]
	v_mfma_scale_f32_16x16x128_f8f6f4 v[52:55], v[28:35], v[212:219], v[52:55], v242, v242 op_sel_hi:[0,0,0]
	s_nop 0
	s_nop 0
	v_mfma_scale_f32_16x16x128_f8f6f4 v[80:83], v[4:11], v[168:175], v[80:83], v242, v242 op_sel_hi:[0,0,0]
	v_mfma_scale_f32_16x16x128_f8f6f4 v[76:79], v[12:19], v[168:175], v[76:79], v242, v242 op_sel_hi:[0,0,0]
	v_mfma_scale_f32_16x16x128_f8f6f4 v[72:75], v[4:11], v[196:203], v[72:75], v242, v242 op_sel_hi:[0,0,0]
	v_mfma_scale_f32_16x16x128_f8f6f4 v[68:71], v[12:19], v[196:203], v[68:71], v242, v242 op_sel_hi:[0,0,0]
	v_mfma_scale_f32_16x16x128_f8f6f4 v[48:51], v[4:11], v[204:211], v[48:51], v242, v242 op_sel_hi:[0,0,0]
	v_mfma_scale_f32_16x16x128_f8f6f4 v[44:47], v[12:19], v[204:211], v[44:47], v242, v242 op_sel_hi:[0,0,0]
	v_mfma_scale_f32_16x16x128_f8f6f4 v[40:43], v[4:11], v[212:219], v[40:43], v242, v242 op_sel_hi:[0,0,0]
	v_mfma_scale_f32_16x16x128_f8f6f4 v[36:39], v[12:19], v[212:219], v[36:39], v242, v242 op_sel_hi:[0,0,0]
	s_nop 0
	s_barrier
; #define G_STAGE(bufoff, gbase, voff) do { _Pragma("unroll") for (int _i = 0; _i < 2; ++_i) \
;         __builtin_amdgcn_global_load_lds((const unsigned*)((const char*)(gbase) + (voff)[_i]), (LAS unsigned*)(lds + (bufoff) + ldsw + _i * 8192), 16, 0, 0); } while (0)
; #define G_LDA(dst, b, h) do { _Pragma("unroll") for (int m = 0; m < 4; ++m) { const i32x4 _p0 = *(const LAS i32x4*)(lds + G_SA(b, h) + aoff + m * 2048), _p1 = *(const LAS i32x4*)(lds + G_SA(b, h) + aoff + m * 2048 + 1024); \
;         dst[m] = __builtin_shufflevector(_p0, _p1, 0, 1, 2, 3, 4, 5, 6, 7); } } while (0)
; #define G_WAIT_V(n) asm volatile("s_waitcnt vmcnt(" #n ")" ::: "memory")
; #define G_WAIT_L(n) asm volatile("s_waitcnt lgkmcnt(" #n ")" ::: "memory")
; #define G_BAR __builtin_amdgcn_s_barrier()
; #define G_SCHED __builtin_amdgcn_sched_barrier(0)
; template <int NS, int MODE  , class Epi>
; __device__ __forceinline__ void gemm_phase(LAS unsigned char* lds, const Gemm g, const StaticOrder& S, const Epi& E) {
;     ...
;         for (int t = 0; t < NT; t += 2) {
;     ...
;             G_WAIT_V(8); G_WAIT_L(0); G_BAR; G_MMA(0, 0, At, B0); G_MMA(0, 1, At, B1); G_BAR; G_SCHED;
;             G_LDA(At, 1, 1); G_STAGE(G_SB(1, 0), b3, voffB); G_STAGE(G_SB(1, 1), b3 + hstep, voffB); G_STAGE(G_SA(1, 0), a3, voffA);
;             G_WAIT_V(8); G_WAIT_L(0); G_BAR; G_MMA(1, 0, At, B0); G_MMA(1, 1, At, B1); G_BAR; G_SCHED;
	s_add_i32 s25, 0, 0x18000
	s_add_i32 s35, 0, 0x1c000
	v_add_u32_e32 v16, s25, v244
	v_add_u32_e32 v32, s35, v244
	ds_read_b128 v[4:7], v16
	ds_read_b128 v[8:11], v16 offset:1024
	ds_read_b128 v[12:15], v16 offset:2048
	ds_read_b128 v[16:19], v16 offset:3072
	ds_read_b128 v[20:23], v32
	ds_read_b128 v[24:27], v32 offset:1024
	ds_read_b128 v[28:31], v32 offset:2048
	ds_read_b128 v[32:35], v32 offset:3072
	s_add_u32 s30, s58, 0xb0000
	s_addc_u32 s31, s59, 0
	s_mov_b32 m0, s56
	v_lshl_add_u64 v[176:177], s[30:31], 0, v[190:191]
	ds_read_b128 v[168:171], v246 offset:32768
	ds_read_b128 v[172:175], v246 offset:33792
	ds_read_b128 v[196:199], v246 offset:34816
	ds_read_b128 v[200:203], v246 offset:35840
	ds_read_b128 v[204:207], v246 offset:36864
	ds_read_b128 v[208:211], v246 offset:37888
	ds_read_b128 v[212:215], v246 offset:38912
	ds_read_b128 v[216:219], v246 offset:39936
	global_load_lds_dwordx4 v[176:177], off
	v_lshl_add_u64 v[176:177], s[30:31], 0, v[188:189]
	s_mov_b32 m0, s62
	s_nop 0
	global_load_lds_dwordx4 v[176:177], off
	s_waitcnt vmcnt(8)
	s_waitcnt lgkmcnt(0)
	s_nop 0
	s_waitcnt lgkmcnt(0)
	v_mfma_scale_f32_16x16x128_f8f6f4 v[160:163], v[4:11], v[168:175], v[160:163], v242, v242 op_sel_hi:[0,0,0]
	v_mfma_scale_f32_16x16x128_f8f6f4 v[156:159], v[12:19], v[168:175], v[156:159], v242, v242 op_sel_hi:[0,0,0]
	v_mfma_scale_f32_16x16x128_f8f6f4 v[148:151], v[4:11], v[196:203], v[148:151], v242, v242 op_sel_hi:[0,0,0]
	v_mfma_scale_f32_16x16x128_f8f6f4 v[144:147], v[12:19], v[196:203], v[144:147], v242, v242 op_sel_hi:[0,0,0]
	s_barrier
	v_mfma_scale_f32_16x16x128_f8f6f4 v[128:131], v[4:11], v[204:211], v[128:131], v242, v242 op_sel_hi:[0,0,0]
	v_mfma_scale_f32_16x16x128_f8f6f4 v[124:127], v[12:19], v[204:211], v[124:127], v242, v242 op_sel_hi:[0,0,0]
	v_mfma_scale_f32_16x16x128_f8f6f4 v[120:123], v[4:11], v[212:219], v[120:123], v242, v242 op_sel_hi:[0,0,0]
	v_mfma_scale_f32_16x16x128_f8f6f4 v[116:119], v[12:19], v[212:219], v[116:119], v242, v242 op_sel_hi:[0,0,0]
	s_nop 0
	s_nop 0
	v_mfma_scale_f32_16x16x128_f8f6f4 v[152:155], v[20:27], v[168:175], v[152:155], v242, v242 op_sel_hi:[0,0,0]
	v_mfma_scale_f32_16x16x128_f8f6f4 v[140:143], v[28:35], v[168:175], v[140:143], v242, v242 op_sel_hi:[0,0,0]
	v_mfma_scale_f32_16x16x128_f8f6f4 v[136:139], v[20:27], v[196:203], v[136:139], v242, v242 op_sel_hi:[0,0,0]
	v_mfma_scale_f32_16x16x128_f8f6f4 v[132:135], v[28:35], v[196:203], v[132:135], v242, v242 op_sel_hi:[0,0,0]
	v_mfma_scale_f32_16x16x128_f8f6f4 v[112:115], v[20:27], v[204:211], v[112:115], v242, v242 op_sel_hi:[0,0,0]
	v_mfma_scale_f32_16x16x128_f8f6f4 v[108:111], v[28:35], v[204:211], v[108:111], v242, v242 op_sel_hi:[0,0,0]
	v_mfma_scale_f32_16x16x128_f8f6f4 v[104:107], v[20:27], v[212:219], v[104:107], v242, v242 op_sel_hi:[0,0,0]
	v_mfma_scale_f32_16x16x128_f8f6f4 v[100:103], v[28:35], v[212:219], v[100:103], v242, v242 op_sel_hi:[0,0,0]
	s_nop 0
	s_barrier
	s_add_i32 s25, s25, s18
	v_lshl_add_u64 v[176:177], s[54:55], 0, v[2:3]
	s_mov_b32 m0, s25
	ds_read_b128 v[168:171], v246 offset:49152
	ds_read_b128 v[172:175], v246 offset:50176
	ds_read_b128 v[196:199], v246 offset:51200
	ds_read_b128 v[200:203], v246 offset:52224
	ds_read_b128 v[204:207], v246 offset:53248
	ds_read_b128 v[208:211], v246 offset:54272
	ds_read_b128 v[212:215], v246 offset:55296
	ds_read_b128 v[216:219], v246 offset:56320
	global_load_lds_dwordx4 v[176:177], off
	s_add_i32 m0, s25, 0x2000
	s_add_u32 s30, s54, 0xb0000
	v_lshl_add_u64 v[176:177], s[54:55], 0, v[186:187]
	s_addc_u32 s31, s55, 0
	s_add_i32 s25, s35, s18
	global_load_lds_dwordx4 v[176:177], off
	v_lshl_add_u64 v[176:177], s[30:31], 0, v[2:3]
	s_mov_b32 m0, s25
	s_nop 0
	global_load_lds_dwordx4 v[176:177], off
	v_lshl_add_u64 v[176:177], s[30:31], 0, v[186:187]
	s_add_i32 m0, s25, 0x2000
	s_nop 0
	global_load_lds_dwordx4 v[176:177], off
	v_lshl_add_u64 v[176:177], s[52:53], 0, v[190:191]
	s_mov_b32 m0, s65
	s_nop 0
	global_load_lds_dwordx4 v[176:177], off
	v_lshl_add_u64 v[176:177], s[52:53], 0, v[188:189]
	s_mov_b32 m0, s66
	s_nop 0
	global_load_lds_dwordx4 v[176:177], off
	s_waitcnt vmcnt(8)
	s_waitcnt lgkmcnt(0)
	s_nop 0
	s_waitcnt lgkmcnt(0)
	v_mfma_scale_f32_16x16x128_f8f6f4 v[96:99], v[4:11], v[168:175], v[96:99], v242, v242 op_sel_hi:[0,0,0]
	v_mfma_scale_f32_16x16x128_f8f6f4 v[92:95], v[12:19], v[168:175], v[92:95], v242, v242 op_sel_hi:[0,0,0]
	v_mfma_scale_f32_16x16x128_f8f6f4 v[88:91], v[4:11], v[196:203], v[88:91], v242, v242 op_sel_hi:[0,0,0]
	v_mfma_scale_f32_16x16x128_f8f6f4 v[84:87], v[12:19], v[196:203], v[84:87], v242, v242 op_sel_hi:[0,0,0]
	s_barrier
	v_mfma_scale_f32_16x16x128_f8f6f4 v[64:67], v[4:11], v[204:211], v[64:67], v242, v242 op_sel_hi:[0,0,0]
	v_mfma_scale_f32_16x16x128_f8f6f4 v[60:63], v[12:19], v[204:211], v[60:63], v242, v242 op_sel_hi:[0,0,0]
	v_mfma_scale_f32_16x16x128_f8f6f4 v[56:59], v[4:11], v[212:219], v[56:59], v242, v242 op_sel_hi:[0,0,0]
	v_mfma_scale_f32_16x16x128_f8f6f4 v[52:55], v[12:19], v[212:219], v[52:55], v242, v242 op_sel_hi:[0,0,0]
	s_nop 0
	s_nop 0
	v_mfma_scale_f32_16x16x128_f8f6f4 v[80:83], v[20:27], v[168:175], v[80:83], v242, v242 op_sel_hi:[0,0,0]
	v_mfma_scale_f32_16x16x128_f8f6f4 v[76:79], v[28:35], v[168:175], v[76:79], v242, v242 op_sel_hi:[0,0,0]
	v_mfma_scale_f32_16x16x128_f8f6f4 v[72:75], v[20:27], v[196:203], v[72:75], v242, v242 op_sel_hi:[0,0,0]
	v_mfma_scale_f32_16x16x128_f8f6f4 v[68:71], v[28:35], v[196:203], v[68:71], v242, v242 op_sel_hi:[0,0,0]
	v_mfma_scale_f32_16x16x128_f8f6f4 v[48:51], v[20:27], v[204:211], v[48:51], v242, v242 op_sel_hi:[0,0,0]
	v_mfma_scale_f32_16x16x128_f8f6f4 v[44:47], v[28:35], v[204:211], v[44:47], v242, v242 op_sel_hi:[0,0,0]
	v_mfma_scale_f32_16x16x128_f8f6f4 v[40:43], v[20:27], v[212:219], v[40:43], v242, v242 op_sel_hi:[0,0,0]
	v_mfma_scale_f32_16x16x128_f8f6f4 v[36:39], v[28:35], v[212:219], v[36:39], v242, v242 op_sel_hi:[0,0,0]
	s_nop 0
	s_barrier
	s_add_i32 s24, s24, 2
	s_add_u32 s46, s46, 0x100
	s_addc_u32 s47, s47, 0
	s_cmp_gt_u32 s24, 41
	s_cbranch_scc1 .LBB0_528

; #define G_STAGE(bufoff, gbase, voff) do { _Pragma("unroll") for (int _i = 0; _i < 2; ++_i) \
;         __builtin_amdgcn_global_load_lds((const unsigned*)((const char*)(gbase) + (voff)[_i]), (LAS unsigned*)(lds + (bufoff) + ldsw + _i * 8192), 16, 0, 0); } while (0)
; #define G_LDA(dst, b, h) do { _Pragma("unroll") for (int m = 0; m < 4; ++m) { const i32x4 _p0 = *(const LAS i32x4*)(lds + G_SA(b, h) + aoff + m * 2048), _p1 = *(const LAS i32x4*)(lds + G_SA(b, h) + aoff + m * 2048 + 1024); \
;         dst[m] = __builtin_shufflevector(_p0, _p1, 0, 1, 2, 3, 4, 5, 6, 7); } } while (0)
; #define G_LDB(dst, b, h) do { _Pragma("unroll") for (int n = 0; n < 2; ++n) { const i32x4 _p0 = *(const LAS i32x4*)(lds + G_SB(b, h) + boff + n * 2048), _p1 = *(const LAS i32x4*)(lds + G_SB(b, h) + boff + n * 2048 + 1024); \
;         dst[n] = __builtin_shufflevector(_p0, _p1, 0, 1, 2, 3, 4, 5, 6, 7); } } while (0)
; #define G_WAIT_V(n) asm volatile("s_waitcnt vmcnt(" #n ")" ::: "memory")
; #define G_WAIT_L(n) asm volatile("s_waitcnt lgkmcnt(" #n ")" ::: "memory")
; #define G_BAR __builtin_amdgcn_s_barrier()
; #define G_SCHED __builtin_amdgcn_sched_barrier(0)
; template <int NS, int MODE  , class Epi>
; __device__ __forceinline__ void gemm_phase(LAS unsigned char* lds, const Gemm g, const StaticOrder& S, const Epi& E) {
;     ...
;             G_LDB(B0, 0, 0); G_LDB(B1, 0, 1); G_SCHED; G_LDA(At, 0, 0); G_STAGE(G_SA(1, 1), a1 + hstep, voffA);
;             G_WAIT_V(8); G_WAIT_L(0); G_BAR; G_MMA(0, 0, At, B0); G_MMA(0, 1, At, B1); G_BAR; G_SCHED;
;             G_LDA(At, 0, 1); G_STAGE(G_SB(0, 0), b2, voffB); G_STAGE(G_SB(0, 1), b2 + hstep, voffB); G_STAGE(G_SA(0, 0), a2, voffA);
;             G_WAIT_V(8); G_WAIT_L(0); G_BAR; G_MMA(1, 0, At, B0); G_MMA(1, 1, At, B1); G_BAR; G_SCHED;
.LBB0_733:
	s_add_i32 s25, 0, 0x10000
	s_add_i32 s27, 0, 0x14000
	v_add_u32_e32 v132, s25, v191
	v_add_u32_e32 v136, s27, v191
	ds_read_b128 v[160:163], v132
	ds_read_b128 v[148:151], v132 offset:1024
	ds_read_b128 v[156:159], v132 offset:2048
	ds_read_b128 v[152:155], v132 offset:3072
	ds_read_b128 v[144:147], v136
	ds_read_b128 v[132:135], v136 offset:1024
	ds_read_b128 v[140:143], v136 offset:2048
	ds_read_b128 v[136:139], v136 offset:3072
	v_lshl_add_u64 v[218:219], v[174:175], 0, s[72:73]
	s_add_i32 m0, s19, 0xc000
	ds_read_b128 v[176:179], v193
	ds_read_b128 v[180:183], v193 offset:1024
	ds_read_b128 v[194:197], v193 offset:2048
	ds_read_b128 v[198:201], v193 offset:3072
	ds_read_b128 v[202:205], v193 offset:4096
	ds_read_b128 v[206:209], v193 offset:5120
	ds_read_b128 v[210:213], v193 offset:6144
	ds_read_b128 v[214:217], v193 offset:7168
	global_load_lds_dwordx4 v[218:219], off
	v_lshl_add_u64 v[218:219], v[186:187], 0, s[72:73]
	s_add_i32 m0, s19, 0xe000
	s_nop 0
	global_load_lds_dwordx4 v[218:219], off
	s_waitcnt vmcnt(8)
	s_waitcnt lgkmcnt(0)
	s_nop 0
	s_waitcnt lgkmcnt(0)
	v_mfma_i32_16x16x64_i8 v[128:131], v[160:163], v[176:179], v[128:131]
	v_mfma_i32_16x16x64_i8 v[124:127], v[156:159], v[176:179], v[124:127]
	v_mfma_i32_16x16x64_i8 v[116:119], v[160:163], v[194:197], v[116:119]
	v_mfma_i32_16x16x64_i8 v[108:111], v[156:159], v[194:197], v[108:111]
	s_barrier
	v_mfma_i32_16x16x64_i8 v[100:103], v[160:163], v[202:205], v[100:103]
	v_mfma_i32_16x16x64_i8 v[92:95], v[156:159], v[202:205], v[92:95]
	v_mfma_i32_16x16x64_i8 v[84:87], v[160:163], v[210:213], v[84:87]
	v_mfma_i32_16x16x64_i8 v[76:79], v[156:159], v[210:213], v[76:79]
	s_nop 0
	v_mfma_i32_16x16x64_i8 v[128:131], v[148:151], v[180:183], v[128:131]
	v_mfma_i32_16x16x64_i8 v[124:127], v[152:155], v[180:183], v[124:127]
	v_mfma_i32_16x16x64_i8 v[116:119], v[148:151], v[198:201], v[116:119]
	v_mfma_i32_16x16x64_i8 v[108:111], v[152:155], v[198:201], v[108:111]
	v_mfma_i32_16x16x64_i8 v[100:103], v[148:151], v[206:209], v[100:103]
	v_mfma_i32_16x16x64_i8 v[92:95], v[152:155], v[206:209], v[92:95]
	v_mfma_i32_16x16x64_i8 v[84:87], v[148:151], v[214:217], v[84:87]
	v_mfma_i32_16x16x64_i8 v[76:79], v[152:155], v[214:217], v[76:79]
	s_nop 0
	s_nop 0
	v_mfma_i32_16x16x64_i8 v[120:123], v[144:147], v[176:179], v[120:123]
	v_mfma_i32_16x16x64_i8 v[112:115], v[140:143], v[176:179], v[112:115]
	v_mfma_i32_16x16x64_i8 v[104:107], v[144:147], v[194:197], v[104:107]
	v_mfma_i32_16x16x64_i8 v[96:99], v[140:143], v[194:197], v[96:99]
	v_mfma_i32_16x16x64_i8 v[88:91], v[144:147], v[202:205], v[88:91]
	v_mfma_i32_16x16x64_i8 v[80:83], v[140:143], v[202:205], v[80:83]
	v_mfma_i32_16x16x64_i8 v[72:75], v[144:147], v[210:213], v[72:75]
	v_mfma_i32_16x16x64_i8 v[68:71], v[140:143], v[210:213], v[68:71]
	s_nop 0
	v_mfma_i32_16x16x64_i8 v[120:123], v[132:135], v[180:183], v[120:123]
	v_mfma_i32_16x16x64_i8 v[112:115], v[136:139], v[180:183], v[112:115]
	v_mfma_i32_16x16x64_i8 v[104:107], v[132:135], v[198:201], v[104:107]
	v_mfma_i32_16x16x64_i8 v[96:99], v[136:139], v[198:201], v[96:99]
	v_mfma_i32_16x16x64_i8 v[88:91], v[132:135], v[206:209], v[88:91]
	v_mfma_i32_16x16x64_i8 v[80:83], v[136:139], v[206:209], v[80:83]
	v_mfma_i32_16x16x64_i8 v[72:75], v[132:135], v[214:217], v[72:75]
	v_mfma_i32_16x16x64_i8 v[68:71], v[136:139], v[214:217], v[68:71]
	s_nop 0
	s_barrier
	s_add_i32 s25, s25, s3
	v_lshl_add_u64 v[218:219], s[90:91], 0, v[2:3]
	s_mov_b32 m0, s25
	ds_read_b128 v[176:179], v193 offset:16384
	ds_read_b128 v[180:183], v193 offset:17408
	ds_read_b128 v[194:197], v193 offset:18432
	ds_read_b128 v[198:201], v193 offset:19456
	ds_read_b128 v[202:205], v193 offset:20480
	ds_read_b128 v[206:209], v193 offset:21504
	ds_read_b128 v[210:213], v193 offset:22528
	ds_read_b128 v[214:217], v193 offset:23552
	global_load_lds_dwordx4 v[218:219], off
	s_add_i32 m0, s25, 0x2000
	s_add_u32 s30, s90, 0x40000
	v_lshl_add_u64 v[218:219], s[90:91], 0, v[164:165]
	s_addc_u32 s31, s91, 0
	s_add_i32 s25, s27, s3
	global_load_lds_dwordx4 v[218:219], off
	v_lshl_add_u64 v[218:219], s[30:31], 0, v[2:3]
	s_mov_b32 m0, s25
	s_nop 0
	global_load_lds_dwordx4 v[218:219], off
	v_lshl_add_u64 v[218:219], s[30:31], 0, v[164:165]
	s_add_i32 m0, s25, 0x2000
	s_nop 0
	global_load_lds_dwordx4 v[218:219], off
	v_lshl_add_u64 v[218:219], s[80:81], 0, v[168:169]
	s_mov_b32 m0, s19
	s_nop 0
	global_load_lds_dwordx4 v[218:219], off
	v_lshl_add_u64 v[218:219], s[80:81], 0, v[166:167]
	s_mov_b32 m0, s29
	s_nop 0
	global_load_lds_dwordx4 v[218:219], off
	s_waitcnt vmcnt(8)
	s_waitcnt lgkmcnt(0)
	s_nop 0
	s_waitcnt lgkmcnt(0)
	v_mfma_i32_16x16x64_i8 v[64:67], v[160:163], v[176:179], v[64:67]
	v_mfma_i32_16x16x64_i8 v[60:63], v[156:159], v[176:179], v[60:63]
	v_mfma_i32_16x16x64_i8 v[52:55], v[160:163], v[194:197], v[52:55]
	v_mfma_i32_16x16x64_i8 v[44:47], v[156:159], v[194:197], v[44:47]
	s_barrier
; #define G_STAGE(bufoff, gbase, voff) do { _Pragma("unroll") for (int _i = 0; _i < 2; ++_i) \
;         __builtin_amdgcn_global_load_lds((const unsigned*)((const char*)(gbase) + (voff)[_i]), (LAS unsigned*)(lds + (bufoff) + ldsw + _i * 8192), 16, 0, 0); } while (0)
; #define G_LDA(dst, b, h) do { _Pragma("unroll") for (int m = 0; m < 4; ++m) { const i32x4 _p0 = *(const LAS i32x4*)(lds + G_SA(b, h) + aoff + m * 2048), _p1 = *(const LAS i32x4*)(lds + G_SA(b, h) + aoff + m * 2048 + 1024); \
;         dst[m] = __builtin_shufflevector(_p0, _p1, 0, 1, 2, 3, 4, 5, 6, 7); } } while (0)
; #define G_LDB(dst, b, h) do { _Pragma("unroll") for (int n = 0; n < 2; ++n) { const i32x4 _p0 = *(const LAS i32x4*)(lds + G_SB(b, h) + boff + n * 2048), _p1 = *(const LAS i32x4*)(lds + G_SB(b, h) + boff + n * 2048 + 1024); \
;         dst[n] = __builtin_shufflevector(_p0, _p1, 0, 1, 2, 3, 4, 5, 6, 7); } } while (0)
; #define G_WAIT_V(n) asm volatile("s_waitcnt vmcnt(" #n ")" ::: "memory")
; #define G_WAIT_L(n) asm volatile("s_waitcnt lgkmcnt(" #n ")" ::: "memory")
; #define G_BAR __builtin_amdgcn_s_barrier()
; #define G_SCHED __builtin_amdgcn_sched_barrier(0)
; template <int NS, int MODE  , class Epi>
; __device__ __forceinline__ void gemm_phase(LAS unsigned char* lds, const Gemm g, const StaticOrder& S, const Epi& E) {
;     ...
;             G_WAIT_V(8); G_WAIT_L(0); G_BAR; G_MMA(1, 0, At, B0); G_MMA(1, 1, At, B1); G_BAR; G_SCHED;
;             G_LDB(B0, 1, 0); G_LDB(B1, 1, 1); G_SCHED; G_LDA(At, 1, 0); G_STAGE(G_SA(0, 1), a2 + hstep, voffA);
;             G_WAIT_V(8); G_WAIT_L(0); G_BAR; G_MMA(0, 0, At, B0); G_MMA(0, 1, At, B1); G_BAR; G_SCHED;
	v_mfma_i32_16x16x64_i8 v[36:39], v[160:163], v[202:205], v[36:39]
	v_mfma_i32_16x16x64_i8 v[28:31], v[156:159], v[202:205], v[28:31]
	v_mfma_i32_16x16x64_i8 v[20:23], v[160:163], v[210:213], v[20:23]
	v_mfma_i32_16x16x64_i8 v[12:15], v[156:159], v[210:213], v[12:15]
	s_nop 0
	v_mfma_i32_16x16x64_i8 v[64:67], v[148:151], v[180:183], v[64:67]
	v_mfma_i32_16x16x64_i8 v[60:63], v[152:155], v[180:183], v[60:63]
	v_mfma_i32_16x16x64_i8 v[52:55], v[148:151], v[198:201], v[52:55]
	v_mfma_i32_16x16x64_i8 v[44:47], v[152:155], v[198:201], v[44:47]
	v_mfma_i32_16x16x64_i8 v[36:39], v[148:151], v[206:209], v[36:39]
	v_mfma_i32_16x16x64_i8 v[28:31], v[152:155], v[206:209], v[28:31]
	v_mfma_i32_16x16x64_i8 v[20:23], v[148:151], v[214:217], v[20:23]
	v_mfma_i32_16x16x64_i8 v[12:15], v[152:155], v[214:217], v[12:15]
	s_nop 0
	s_nop 0
	v_mfma_i32_16x16x64_i8 v[56:59], v[144:147], v[176:179], v[56:59]
	v_mfma_i32_16x16x64_i8 v[48:51], v[140:143], v[176:179], v[48:51]
	v_mfma_i32_16x16x64_i8 v[40:43], v[144:147], v[194:197], v[40:43]
	v_mfma_i32_16x16x64_i8 v[32:35], v[140:143], v[194:197], v[32:35]
	v_mfma_i32_16x16x64_i8 v[24:27], v[144:147], v[202:205], v[24:27]
	v_mfma_i32_16x16x64_i8 v[16:19], v[140:143], v[202:205], v[16:19]
	v_mfma_i32_16x16x64_i8 v[8:11], v[144:147], v[210:213], v[8:11]
	v_mfma_i32_16x16x64_i8 v[4:7], v[140:143], v[210:213], v[4:7]
	s_nop 0
	v_mfma_i32_16x16x64_i8 v[56:59], v[132:135], v[180:183], v[56:59]
	v_mfma_i32_16x16x64_i8 v[48:51], v[136:139], v[180:183], v[48:51]
	v_mfma_i32_16x16x64_i8 v[40:43], v[132:135], v[198:201], v[40:43]
	v_mfma_i32_16x16x64_i8 v[32:35], v[136:139], v[198:201], v[32:35]
	v_mfma_i32_16x16x64_i8 v[24:27], v[132:135], v[206:209], v[24:27]
	v_mfma_i32_16x16x64_i8 v[16:19], v[136:139], v[206:209], v[16:19]
	v_mfma_i32_16x16x64_i8 v[8:11], v[132:135], v[214:217], v[8:11]
	v_mfma_i32_16x16x64_i8 v[4:7], v[136:139], v[214:217], v[4:7]
	s_nop 0
	s_barrier
	s_add_i32 s25, 0, 0x18000
	s_add_i32 s27, 0, 0x1c000
	v_add_u32_e32 v144, s25, v191
	v_add_u32_e32 v160, s27, v191
	ds_read_b128 v[132:135], v144
	ds_read_b128 v[136:139], v144 offset:1024
	ds_read_b128 v[140:143], v144 offset:2048
	ds_read_b128 v[144:147], v144 offset:3072
	ds_read_b128 v[148:151], v160
	ds_read_b128 v[152:155], v160 offset:1024
	ds_read_b128 v[156:159], v160 offset:2048
	ds_read_b128 v[160:163], v160 offset:3072
	s_add_u32 s30, s80, 0x40000
	s_addc_u32 s31, s81, 0
	s_mov_b32 m0, s35
	v_lshl_add_u64 v[218:219], s[30:31], 0, v[168:169]
	ds_read_b128 v[176:179], v193 offset:32768
	ds_read_b128 v[180:183], v193 offset:33792
	ds_read_b128 v[194:197], v193 offset:34816
	ds_read_b128 v[198:201], v193 offset:35840
	ds_read_b128 v[202:205], v193 offset:36864
	ds_read_b128 v[206:209], v193 offset:37888
	ds_read_b128 v[210:213], v193 offset:38912
	ds_read_b128 v[214:217], v193 offset:39936
	global_load_lds_dwordx4 v[218:219], off
	v_lshl_add_u64 v[218:219], s[30:31], 0, v[166:167]
	s_mov_b32 m0, s59
	s_nop 0
	global_load_lds_dwordx4 v[218:219], off
	s_waitcnt vmcnt(8)
	s_waitcnt lgkmcnt(0)
	s_nop 0
	s_waitcnt lgkmcnt(0)
	v_mfma_i32_16x16x64_i8 v[128:131], v[132:135], v[176:179], v[128:131]
	v_mfma_i32_16x16x64_i8 v[124:127], v[140:143], v[176:179], v[124:127]
	v_mfma_i32_16x16x64_i8 v[116:119], v[132:135], v[194:197], v[116:119]
	v_mfma_i32_16x16x64_i8 v[108:111], v[140:143], v[194:197], v[108:111]
	s_barrier
	v_mfma_i32_16x16x64_i8 v[100:103], v[132:135], v[202:205], v[100:103]
	v_mfma_i32_16x16x64_i8 v[92:95], v[140:143], v[202:205], v[92:95]
	v_mfma_i32_16x16x64_i8 v[84:87], v[132:135], v[210:213], v[84:87]
	v_mfma_i32_16x16x64_i8 v[76:79], v[140:143], v[210:213], v[76:79]
	s_nop 0
	v_mfma_i32_16x16x64_i8 v[128:131], v[136:139], v[180:183], v[128:131]
	v_mfma_i32_16x16x64_i8 v[124:127], v[144:147], v[180:183], v[124:127]
	v_mfma_i32_16x16x64_i8 v[116:119], v[136:139], v[198:201], v[116:119]
	v_mfma_i32_16x16x64_i8 v[108:111], v[144:147], v[198:201], v[108:111]
	v_mfma_i32_16x16x64_i8 v[100:103], v[136:139], v[206:209], v[100:103]
	v_mfma_i32_16x16x64_i8 v[92:95], v[144:147], v[206:209], v[92:95]
	v_mfma_i32_16x16x64_i8 v[84:87], v[136:139], v[214:217], v[84:87]
	v_mfma_i32_16x16x64_i8 v[76:79], v[144:147], v[214:217], v[76:79]
	s_nop 0
	s_nop 0
	v_mfma_i32_16x16x64_i8 v[120:123], v[148:151], v[176:179], v[120:123]
	v_mfma_i32_16x16x64_i8 v[112:115], v[156:159], v[176:179], v[112:115]
	v_mfma_i32_16x16x64_i8 v[104:107], v[148:151], v[194:197], v[104:107]
	v_mfma_i32_16x16x64_i8 v[96:99], v[156:159], v[194:197], v[96:99]
	v_mfma_i32_16x16x64_i8 v[88:91], v[148:151], v[202:205], v[88:91]
	v_mfma_i32_16x16x64_i8 v[80:83], v[156:159], v[202:205], v[80:83]
	v_mfma_i32_16x16x64_i8 v[72:75], v[148:151], v[210:213], v[72:75]
	v_mfma_i32_16x16x64_i8 v[68:71], v[156:159], v[210:213], v[68:71]
	s_nop 0
	v_mfma_i32_16x16x64_i8 v[120:123], v[152:155], v[180:183], v[120:123]
	v_mfma_i32_16x16x64_i8 v[112:115], v[160:163], v[180:183], v[112:115]
	v_mfma_i32_16x16x64_i8 v[104:107], v[152:155], v[198:201], v[104:107]
	v_mfma_i32_16x16x64_i8 v[96:99], v[160:163], v[198:201], v[96:99]
	v_mfma_i32_16x16x64_i8 v[88:91], v[152:155], v[206:209], v[88:91]
	v_mfma_i32_16x16x64_i8 v[80:83], v[160:163], v[206:209], v[80:83]
	v_mfma_i32_16x16x64_i8 v[72:75], v[152:155], v[214:217], v[72:75]
	v_mfma_i32_16x16x64_i8 v[68:71], v[160:163], v[214:217], v[68:71]
	s_nop 0
	s_barrier
; #define G_STAGE(bufoff, gbase, voff) do { _Pragma("unroll") for (int _i = 0; _i < 2; ++_i) \
;         __builtin_amdgcn_global_load_lds((const unsigned*)((const char*)(gbase) + (voff)[_i]), (LAS unsigned*)(lds + (bufoff) + ldsw + _i * 8192), 16, 0, 0); } while (0)
; #define G_LDA(dst, b, h) do { _Pragma("unroll") for (int m = 0; m < 4; ++m) { const i32x4 _p0 = *(const LAS i32x4*)(lds + G_SA(b, h) + aoff + m * 2048), _p1 = *(const LAS i32x4*)(lds + G_SA(b, h) + aoff + m * 2048 + 1024); \
;         dst[m] = __builtin_shufflevector(_p0, _p1, 0, 1, 2, 3, 4, 5, 6, 7); } } while (0)
; #define G_WAIT_V(n) asm volatile("s_waitcnt vmcnt(" #n ")" ::: "memory")
; #define G_WAIT_L(n) asm volatile("s_waitcnt lgkmcnt(" #n ")" ::: "memory")
; #define G_BAR __builtin_amdgcn_s_barrier()
; #define G_SCHED __builtin_amdgcn_sched_barrier(0)
; template <int NS, int MODE  , class Epi>
; __device__ __forceinline__ void gemm_phase(LAS unsigned char* lds, const Gemm g, const StaticOrder& S, const Epi& E) {
;     ...
;         for (int t = 0; t < NT; t += 2) {
;     ...
;             G_LDA(At, 1, 1); G_STAGE(G_SB(1, 0), b3, voffB); G_STAGE(G_SB(1, 1), b3 + hstep, voffB); G_STAGE(G_SA(1, 0), a3, voffA);
;             G_WAIT_V(8); G_WAIT_L(0); G_BAR; G_MMA(1, 0, At, B0); G_MMA(1, 1, At, B1); G_BAR; G_SCHED;
	s_add_i32 s25, s25, s3
	v_lshl_add_u64 v[218:219], s[76:77], 0, v[2:3]
	s_mov_b32 m0, s25
	ds_read_b128 v[176:179], v193 offset:49152
	ds_read_b128 v[180:183], v193 offset:50176
	ds_read_b128 v[194:197], v193 offset:51200
	ds_read_b128 v[198:201], v193 offset:52224
	ds_read_b128 v[202:205], v193 offset:53248
	ds_read_b128 v[206:209], v193 offset:54272
	ds_read_b128 v[210:213], v193 offset:55296
	ds_read_b128 v[214:217], v193 offset:56320
	global_load_lds_dwordx4 v[218:219], off
	s_add_i32 m0, s25, 0x2000
	s_add_u32 s30, s76, 0x40000
	v_lshl_add_u64 v[218:219], s[76:77], 0, v[164:165]
	s_addc_u32 s31, s77, 0
	s_add_i32 s25, s27, s3
	global_load_lds_dwordx4 v[218:219], off
	v_lshl_add_u64 v[218:219], s[30:31], 0, v[2:3]
	s_mov_b32 m0, s25
	s_nop 0
	global_load_lds_dwordx4 v[218:219], off
	v_lshl_add_u64 v[218:219], s[30:31], 0, v[164:165]
	s_add_i32 m0, s25, 0x2000
	s_nop 0
	global_load_lds_dwordx4 v[218:219], off
	v_lshl_add_u64 v[218:219], s[74:75], 0, v[168:169]
	s_mov_b32 m0, s2
	s_nop 0
	global_load_lds_dwordx4 v[218:219], off
	v_lshl_add_u64 v[218:219], s[74:75], 0, v[166:167]
	s_mov_b32 m0, s86
	s_nop 0
	global_load_lds_dwordx4 v[218:219], off
	s_waitcnt vmcnt(8)
	s_waitcnt lgkmcnt(0)
	s_nop 0
	s_waitcnt lgkmcnt(0)
	v_mfma_i32_16x16x64_i8 v[64:67], v[132:135], v[176:179], v[64:67]
	v_mfma_i32_16x16x64_i8 v[60:63], v[140:143], v[176:179], v[60:63]
	v_mfma_i32_16x16x64_i8 v[52:55], v[132:135], v[194:197], v[52:55]
	v_mfma_i32_16x16x64_i8 v[44:47], v[140:143], v[194:197], v[44:47]
	s_barrier
	v_mfma_i32_16x16x64_i8 v[36:39], v[132:135], v[202:205], v[36:39]
	v_mfma_i32_16x16x64_i8 v[28:31], v[140:143], v[202:205], v[28:31]
	v_mfma_i32_16x16x64_i8 v[20:23], v[132:135], v[210:213], v[20:23]
	v_mfma_i32_16x16x64_i8 v[12:15], v[140:143], v[210:213], v[12:15]
	s_nop 0
	v_mfma_i32_16x16x64_i8 v[64:67], v[136:139], v[180:183], v[64:67]
	v_mfma_i32_16x16x64_i8 v[60:63], v[144:147], v[180:183], v[60:63]
	v_mfma_i32_16x16x64_i8 v[52:55], v[136:139], v[198:201], v[52:55]
	v_mfma_i32_16x16x64_i8 v[44:47], v[144:147], v[198:201], v[44:47]
	v_mfma_i32_16x16x64_i8 v[36:39], v[136:139], v[206:209], v[36:39]
	v_mfma_i32_16x16x64_i8 v[28:31], v[144:147], v[206:209], v[28:31]
	v_mfma_i32_16x16x64_i8 v[20:23], v[136:139], v[214:217], v[20:23]
	v_mfma_i32_16x16x64_i8 v[12:15], v[144:147], v[214:217], v[12:15]
	s_nop 0
	s_nop 0
	v_mfma_i32_16x16x64_i8 v[56:59], v[148:151], v[176:179], v[56:59]
	v_mfma_i32_16x16x64_i8 v[48:51], v[156:159], v[176:179], v[48:51]
	v_mfma_i32_16x16x64_i8 v[40:43], v[148:151], v[194:197], v[40:43]
	v_mfma_i32_16x16x64_i8 v[32:35], v[156:159], v[194:197], v[32:35]
	v_mfma_i32_16x16x64_i8 v[24:27], v[148:151], v[202:205], v[24:27]
	v_mfma_i32_16x16x64_i8 v[16:19], v[156:159], v[202:205], v[16:19]
	v_mfma_i32_16x16x64_i8 v[8:11], v[148:151], v[210:213], v[8:11]
	v_mfma_i32_16x16x64_i8 v[4:7], v[156:159], v[210:213], v[4:7]
	s_nop 0
	v_mfma_i32_16x16x64_i8 v[56:59], v[152:155], v[180:183], v[56:59]
	v_mfma_i32_16x16x64_i8 v[48:51], v[160:163], v[180:183], v[48:51]
	v_mfma_i32_16x16x64_i8 v[40:43], v[152:155], v[198:201], v[40:43]
	v_mfma_i32_16x16x64_i8 v[32:35], v[160:163], v[198:201], v[32:35]
	v_mfma_i32_16x16x64_i8 v[24:27], v[152:155], v[206:209], v[24:27]
	v_mfma_i32_16x16x64_i8 v[16:19], v[160:163], v[206:209], v[16:19]
	v_mfma_i32_16x16x64_i8 v[8:11], v[152:155], v[214:217], v[8:11]
	v_mfma_i32_16x16x64_i8 v[4:7], v[160:163], v[214:217], v[4:7]
	s_nop 0
	s_barrier
	s_add_i32 s21, s21, 2
	s_add_u32 s72, s72, 0x100
	s_addc_u32 s73, s73, 0
	s_cmp_gt_u32 s21, 13
	s_cbranch_scc1 .LBB0_736

; #define G_STAGE(bufoff, gbase, voff) do { _Pragma("unroll") for (int _i = 0; _i < 2; ++_i) \
;         __builtin_amdgcn_global_load_lds((const unsigned*)((const char*)(gbase) + (voff)[_i]), (LAS unsigned*)(lds + (bufoff) + ldsw + _i * 8192), 16, 0, 0); } while (0)
; #define G_LDA(dst, b, h) do { _Pragma("unroll") for (int m = 0; m < 4; ++m) { const i32x4 _p0 = *(const LAS i32x4*)(lds + G_SA(b, h) + aoff + m * 2048), _p1 = *(const LAS i32x4*)(lds + G_SA(b, h) + aoff + m * 2048 + 1024); \
;         dst[m] = __builtin_shufflevector(_p0, _p1, 0, 1, 2, 3, 4, 5, 6, 7); } } while (0)
; #define G_LDB(dst, b, h) do { _Pragma("unroll") for (int n = 0; n < 2; ++n) { const i32x4 _p0 = *(const LAS i32x4*)(lds + G_SB(b, h) + boff + n * 2048), _p1 = *(const LAS i32x4*)(lds + G_SB(b, h) + boff + n * 2048 + 1024); \
;         dst[n] = __builtin_shufflevector(_p0, _p1, 0, 1, 2, 3, 4, 5, 6, 7); } } while (0)
; #define G_WAIT_V(n) asm volatile("s_waitcnt vmcnt(" #n ")" ::: "memory")
; #define G_WAIT_L(n) asm volatile("s_waitcnt lgkmcnt(" #n ")" ::: "memory")
; #define G_BAR __builtin_amdgcn_s_barrier()
; #define G_SCHED __builtin_amdgcn_sched_barrier(0)
; template <int NS, int MODE  , class Epi>
; __device__ __forceinline__ void gemm_phase(LAS unsigned char* lds, const Gemm g, const StaticOrder& S, const Epi& E) {
;     ...
;             G_LDB(B0, 0, 0); G_LDB(B1, 0, 1); G_SCHED; G_LDA(At, 0, 0); G_STAGE(G_SA(1, 1), a1 + hstep, voffA);
;             G_WAIT_V(8); G_WAIT_L(0); G_BAR; G_MMA(0, 0, At, B0); G_MMA(0, 1, At, B1); G_BAR; G_SCHED;
;             G_LDA(At, 0, 1); G_STAGE(G_SB(0, 0), b2, voffB); G_STAGE(G_SB(0, 1), b2 + hstep, voffB); G_STAGE(G_SA(0, 0), a2, voffA);
;             G_WAIT_V(8); G_WAIT_L(0); G_BAR; G_MMA(1, 0, At, B0); G_MMA(1, 1, At, B1); G_BAR; G_SCHED;
.LBB0_753:
	s_add_i32 s25, 0, 0x10000
	s_add_i32 s27, 0, 0x14000
	v_add_u32_e32 v162, s25, v147
	v_add_u32_e32 v178, s27, v147
	ds_read_b128 v[150:153], v162
	ds_read_b128 v[154:157], v162 offset:1024
	ds_read_b128 v[158:161], v162 offset:2048
	ds_read_b128 v[162:165], v162 offset:3072
	ds_read_b128 v[166:169], v178
	ds_read_b128 v[170:173], v178 offset:1024
	ds_read_b128 v[174:177], v178 offset:2048
	ds_read_b128 v[178:181], v178 offset:3072
	v_lshl_add_u64 v[182:183], v[142:143], 0, s[72:73]
	s_add_i32 m0, s3, 0xc000
	ds_read_b128 v[190:193], v149
	ds_read_b128 v[194:197], v149 offset:1024
	ds_read_b128 v[198:201], v149 offset:2048
	ds_read_b128 v[202:205], v149 offset:3072
	ds_read_b128 v[206:209], v149 offset:4096
	ds_read_b128 v[210:213], v149 offset:5120
	ds_read_b128 v[214:217], v149 offset:6144
	ds_read_b128 v[218:221], v149 offset:7168
	global_load_lds_dwordx4 v[182:183], off
	v_lshl_add_u64 v[182:183], v[144:145], 0, s[72:73]
	s_add_i32 m0, s3, 0xe000
	s_nop 0
	global_load_lds_dwordx4 v[182:183], off
	s_waitcnt vmcnt(8)
	s_waitcnt lgkmcnt(0)
	s_nop 0
	s_waitcnt lgkmcnt(0)
	v_mfma_f32_16x16x32_f16 v[128:131], v[150:153], v[190:193], v[128:131]
	v_mfma_f32_16x16x32_f16 v[124:127], v[158:161], v[190:193], v[124:127]
	v_mfma_f32_16x16x32_f16 v[116:119], v[150:153], v[198:201], v[116:119]
	v_mfma_f32_16x16x32_f16 v[108:111], v[158:161], v[198:201], v[108:111]
	s_barrier
	v_mfma_f32_16x16x32_f16 v[100:103], v[150:153], v[206:209], v[100:103]
	v_mfma_f32_16x16x32_f16 v[92:95], v[158:161], v[206:209], v[92:95]
	v_mfma_f32_16x16x32_f16 v[84:87], v[150:153], v[214:217], v[84:87]
	v_mfma_f32_16x16x32_f16 v[76:79], v[158:161], v[214:217], v[76:79]
	v_mfma_f32_16x16x32_f16 v[128:131], v[154:157], v[194:197], v[128:131]
	v_mfma_f32_16x16x32_f16 v[124:127], v[162:165], v[194:197], v[124:127]
	v_mfma_f32_16x16x32_f16 v[116:119], v[154:157], v[202:205], v[116:119]
	v_mfma_f32_16x16x32_f16 v[108:111], v[162:165], v[202:205], v[108:111]
	v_mfma_f32_16x16x32_f16 v[100:103], v[154:157], v[210:213], v[100:103]
	v_mfma_f32_16x16x32_f16 v[92:95], v[162:165], v[210:213], v[92:95]
	v_mfma_f32_16x16x32_f16 v[84:87], v[154:157], v[218:221], v[84:87]
	v_mfma_f32_16x16x32_f16 v[76:79], v[162:165], v[218:221], v[76:79]
	s_nop 0
	s_nop 0
	v_mfma_f32_16x16x32_f16 v[120:123], v[166:169], v[190:193], v[120:123]
	v_mfma_f32_16x16x32_f16 v[112:115], v[174:177], v[190:193], v[112:115]
	v_mfma_f32_16x16x32_f16 v[104:107], v[166:169], v[198:201], v[104:107]
	v_mfma_f32_16x16x32_f16 v[96:99], v[174:177], v[198:201], v[96:99]
	v_mfma_f32_16x16x32_f16 v[88:91], v[166:169], v[206:209], v[88:91]
	v_mfma_f32_16x16x32_f16 v[80:83], v[174:177], v[206:209], v[80:83]
	v_mfma_f32_16x16x32_f16 v[72:75], v[166:169], v[214:217], v[72:75]
	v_mfma_f32_16x16x32_f16 v[68:71], v[174:177], v[214:217], v[68:71]
	v_mfma_f32_16x16x32_f16 v[120:123], v[170:173], v[194:197], v[120:123]
	v_mfma_f32_16x16x32_f16 v[112:115], v[178:181], v[194:197], v[112:115]
	v_mfma_f32_16x16x32_f16 v[104:107], v[170:173], v[202:205], v[104:107]
	v_mfma_f32_16x16x32_f16 v[96:99], v[178:181], v[202:205], v[96:99]
	v_mfma_f32_16x16x32_f16 v[88:91], v[170:173], v[210:213], v[88:91]
	v_mfma_f32_16x16x32_f16 v[80:83], v[178:181], v[210:213], v[80:83]
	v_mfma_f32_16x16x32_f16 v[72:75], v[170:173], v[218:221], v[72:75]
	v_mfma_f32_16x16x32_f16 v[68:71], v[178:181], v[218:221], v[68:71]
	s_nop 0
	s_barrier
	s_add_i32 s25, s25, s2
	v_lshl_add_u64 v[182:183], s[90:91], 0, v[2:3]
	s_mov_b32 m0, s25
	ds_read_b128 v[190:193], v149 offset:16384
	ds_read_b128 v[194:197], v149 offset:17408
	ds_read_b128 v[198:201], v149 offset:18432
	ds_read_b128 v[202:205], v149 offset:19456
	ds_read_b128 v[206:209], v149 offset:20480
	ds_read_b128 v[210:213], v149 offset:21504
	ds_read_b128 v[214:217], v149 offset:22528
	ds_read_b128 v[218:221], v149 offset:23552
	global_load_lds_dwordx4 v[182:183], off
	s_add_i32 m0, s25, 0x2000
	s_add_u32 s30, s90, 0x80000
	v_lshl_add_u64 v[182:183], s[90:91], 0, v[132:133]
	s_addc_u32 s31, s91, 0
	s_add_i32 s25, s27, s2
	global_load_lds_dwordx4 v[182:183], off
	v_lshl_add_u64 v[182:183], s[30:31], 0, v[2:3]
	s_mov_b32 m0, s25
	s_nop 0
	global_load_lds_dwordx4 v[182:183], off
	v_lshl_add_u64 v[182:183], s[30:31], 0, v[132:133]
	s_add_i32 m0, s25, 0x2000
	s_nop 0
	global_load_lds_dwordx4 v[182:183], off
	v_lshl_add_u64 v[182:183], s[80:81], 0, v[136:137]
	s_mov_b32 m0, s3
	s_nop 0
	global_load_lds_dwordx4 v[182:183], off
	v_lshl_add_u64 v[182:183], s[80:81], 0, v[134:135]
	s_mov_b32 m0, s18
	s_nop 0
	global_load_lds_dwordx4 v[182:183], off
	s_waitcnt vmcnt(8)
	s_waitcnt lgkmcnt(0)
	s_nop 0
	s_waitcnt lgkmcnt(0)
	v_mfma_f32_16x16x32_f16 v[64:67], v[150:153], v[190:193], v[64:67]
	v_mfma_f32_16x16x32_f16 v[60:63], v[158:161], v[190:193], v[60:63]
	v_mfma_f32_16x16x32_f16 v[52:55], v[150:153], v[198:201], v[52:55]
	v_mfma_f32_16x16x32_f16 v[44:47], v[158:161], v[198:201], v[44:47]
	s_barrier
; #define G_STAGE(bufoff, gbase, voff) do { _Pragma("unroll") for (int _i = 0; _i < 2; ++_i) \
;         __builtin_amdgcn_global_load_lds((const unsigned*)((const char*)(gbase) + (voff)[_i]), (LAS unsigned*)(lds + (bufoff) + ldsw + _i * 8192), 16, 0, 0); } while (0)
; #define G_LDA(dst, b, h) do { _Pragma("unroll") for (int m = 0; m < 4; ++m) { const i32x4 _p0 = *(const LAS i32x4*)(lds + G_SA(b, h) + aoff + m * 2048), _p1 = *(const LAS i32x4*)(lds + G_SA(b, h) + aoff + m * 2048 + 1024); \
;         dst[m] = __builtin_shufflevector(_p0, _p1, 0, 1, 2, 3, 4, 5, 6, 7); } } while (0)
; #define G_LDB(dst, b, h) do { _Pragma("unroll") for (int n = 0; n < 2; ++n) { const i32x4 _p0 = *(const LAS i32x4*)(lds + G_SB(b, h) + boff + n * 2048), _p1 = *(const LAS i32x4*)(lds + G_SB(b, h) + boff + n * 2048 + 1024); \
;         dst[n] = __builtin_shufflevector(_p0, _p1, 0, 1, 2, 3, 4, 5, 6, 7); } } while (0)
; #define G_WAIT_V(n) asm volatile("s_waitcnt vmcnt(" #n ")" ::: "memory")
; #define G_WAIT_L(n) asm volatile("s_waitcnt lgkmcnt(" #n ")" ::: "memory")
; #define G_BAR __builtin_amdgcn_s_barrier()
; #define G_SCHED __builtin_amdgcn_sched_barrier(0)
; template <int NS, int MODE  , class Epi>
; __device__ __forceinline__ void gemm_phase(LAS unsigned char* lds, const Gemm g, const StaticOrder& S, const Epi& E) {
;     ...
;             G_WAIT_V(8); G_WAIT_L(0); G_BAR; G_MMA(1, 0, At, B0); G_MMA(1, 1, At, B1); G_BAR; G_SCHED;
;             G_LDB(B0, 1, 0); G_LDB(B1, 1, 1); G_SCHED; G_LDA(At, 1, 0); G_STAGE(G_SA(0, 1), a2 + hstep, voffA);
;             G_WAIT_V(8); G_WAIT_L(0); G_BAR; G_MMA(0, 0, At, B0); G_MMA(0, 1, At, B1); G_BAR; G_SCHED;
	v_mfma_f32_16x16x32_f16 v[36:39], v[150:153], v[206:209], v[36:39]
	v_mfma_f32_16x16x32_f16 v[28:31], v[158:161], v[206:209], v[28:31]
	v_mfma_f32_16x16x32_f16 v[20:23], v[150:153], v[214:217], v[20:23]
	v_mfma_f32_16x16x32_f16 v[12:15], v[158:161], v[214:217], v[12:15]
	v_mfma_f32_16x16x32_f16 v[64:67], v[154:157], v[194:197], v[64:67]
	v_mfma_f32_16x16x32_f16 v[60:63], v[162:165], v[194:197], v[60:63]
	v_mfma_f32_16x16x32_f16 v[52:55], v[154:157], v[202:205], v[52:55]
	v_mfma_f32_16x16x32_f16 v[44:47], v[162:165], v[202:205], v[44:47]
	v_mfma_f32_16x16x32_f16 v[36:39], v[154:157], v[210:213], v[36:39]
	v_mfma_f32_16x16x32_f16 v[28:31], v[162:165], v[210:213], v[28:31]
	v_mfma_f32_16x16x32_f16 v[20:23], v[154:157], v[218:221], v[20:23]
	v_mfma_f32_16x16x32_f16 v[12:15], v[162:165], v[218:221], v[12:15]
	s_nop 0
	s_nop 0
	v_mfma_f32_16x16x32_f16 v[56:59], v[166:169], v[190:193], v[56:59]
	v_mfma_f32_16x16x32_f16 v[48:51], v[174:177], v[190:193], v[48:51]
	v_mfma_f32_16x16x32_f16 v[40:43], v[166:169], v[198:201], v[40:43]
	v_mfma_f32_16x16x32_f16 v[32:35], v[174:177], v[198:201], v[32:35]
	v_mfma_f32_16x16x32_f16 v[24:27], v[166:169], v[206:209], v[24:27]
	v_mfma_f32_16x16x32_f16 v[16:19], v[174:177], v[206:209], v[16:19]
	v_mfma_f32_16x16x32_f16 v[8:11], v[166:169], v[214:217], v[8:11]
	v_mfma_f32_16x16x32_f16 v[4:7], v[174:177], v[214:217], v[4:7]
	v_mfma_f32_16x16x32_f16 v[56:59], v[170:173], v[194:197], v[56:59]
	v_mfma_f32_16x16x32_f16 v[48:51], v[178:181], v[194:197], v[48:51]
	v_mfma_f32_16x16x32_f16 v[40:43], v[170:173], v[202:205], v[40:43]
	v_mfma_f32_16x16x32_f16 v[32:35], v[178:181], v[202:205], v[32:35]
	v_mfma_f32_16x16x32_f16 v[24:27], v[170:173], v[210:213], v[24:27]
	v_mfma_f32_16x16x32_f16 v[16:19], v[178:181], v[210:213], v[16:19]
	v_mfma_f32_16x16x32_f16 v[8:11], v[170:173], v[218:221], v[8:11]
	v_mfma_f32_16x16x32_f16 v[4:7], v[178:181], v[218:221], v[4:7]
	s_nop 0
	s_barrier
	s_add_i32 s25, 0, 0x18000
	s_add_i32 s27, 0, 0x1c000
	v_add_u32_e32 v162, s25, v147
	v_add_u32_e32 v178, s27, v147
	ds_read_b128 v[150:153], v162
	ds_read_b128 v[154:157], v162 offset:1024
	ds_read_b128 v[158:161], v162 offset:2048
	ds_read_b128 v[162:165], v162 offset:3072
	ds_read_b128 v[166:169], v178
	ds_read_b128 v[170:173], v178 offset:1024
	ds_read_b128 v[174:177], v178 offset:2048
	ds_read_b128 v[178:181], v178 offset:3072
	s_add_u32 s30, s80, 0x80000
	s_addc_u32 s31, s81, 0
	s_mov_b32 m0, s19
	v_lshl_add_u64 v[182:183], s[30:31], 0, v[136:137]
	ds_read_b128 v[190:193], v149 offset:32768
	ds_read_b128 v[194:197], v149 offset:33792
	ds_read_b128 v[198:201], v149 offset:34816
	ds_read_b128 v[202:205], v149 offset:35840
	ds_read_b128 v[206:209], v149 offset:36864
	ds_read_b128 v[210:213], v149 offset:37888
	ds_read_b128 v[214:217], v149 offset:38912
	ds_read_b128 v[218:221], v149 offset:39936
	global_load_lds_dwordx4 v[182:183], off
	v_lshl_add_u64 v[182:183], s[30:31], 0, v[134:135]
	s_mov_b32 m0, s29
	s_nop 0
	global_load_lds_dwordx4 v[182:183], off
	s_waitcnt vmcnt(8)
	s_waitcnt lgkmcnt(0)
	s_nop 0
	s_waitcnt lgkmcnt(0)
	v_mfma_f32_16x16x32_f16 v[128:131], v[150:153], v[190:193], v[128:131]
	v_mfma_f32_16x16x32_f16 v[124:127], v[158:161], v[190:193], v[124:127]
	v_mfma_f32_16x16x32_f16 v[116:119], v[150:153], v[198:201], v[116:119]
	v_mfma_f32_16x16x32_f16 v[108:111], v[158:161], v[198:201], v[108:111]
	s_barrier
	v_mfma_f32_16x16x32_f16 v[100:103], v[150:153], v[206:209], v[100:103]
	v_mfma_f32_16x16x32_f16 v[92:95], v[158:161], v[206:209], v[92:95]
	v_mfma_f32_16x16x32_f16 v[84:87], v[150:153], v[214:217], v[84:87]
	v_mfma_f32_16x16x32_f16 v[76:79], v[158:161], v[214:217], v[76:79]
	v_mfma_f32_16x16x32_f16 v[128:131], v[154:157], v[194:197], v[128:131]
	v_mfma_f32_16x16x32_f16 v[124:127], v[162:165], v[194:197], v[124:127]
	v_mfma_f32_16x16x32_f16 v[116:119], v[154:157], v[202:205], v[116:119]
	v_mfma_f32_16x16x32_f16 v[108:111], v[162:165], v[202:205], v[108:111]
	v_mfma_f32_16x16x32_f16 v[100:103], v[154:157], v[210:213], v[100:103]
	v_mfma_f32_16x16x32_f16 v[92:95], v[162:165], v[210:213], v[92:95]
	v_mfma_f32_16x16x32_f16 v[84:87], v[154:157], v[218:221], v[84:87]
	v_mfma_f32_16x16x32_f16 v[76:79], v[162:165], v[218:221], v[76:79]
	s_nop 0
	s_nop 0
	v_mfma_f32_16x16x32_f16 v[120:123], v[166:169], v[190:193], v[120:123]
	v_mfma_f32_16x16x32_f16 v[112:115], v[174:177], v[190:193], v[112:115]
	v_mfma_f32_16x16x32_f16 v[104:107], v[166:169], v[198:201], v[104:107]
	v_mfma_f32_16x16x32_f16 v[96:99], v[174:177], v[198:201], v[96:99]
	v_mfma_f32_16x16x32_f16 v[88:91], v[166:169], v[206:209], v[88:91]
	v_mfma_f32_16x16x32_f16 v[80:83], v[174:177], v[206:209], v[80:83]
	v_mfma_f32_16x16x32_f16 v[72:75], v[166:169], v[214:217], v[72:75]
	v_mfma_f32_16x16x32_f16 v[68:71], v[174:177], v[214:217], v[68:71]
	v_mfma_f32_16x16x32_f16 v[120:123], v[170:173], v[194:197], v[120:123]
	v_mfma_f32_16x16x32_f16 v[112:115], v[178:181], v[194:197], v[112:115]
	v_mfma_f32_16x16x32_f16 v[104:107], v[170:173], v[202:205], v[104:107]
	v_mfma_f32_16x16x32_f16 v[96:99], v[178:181], v[202:205], v[96:99]
	v_mfma_f32_16x16x32_f16 v[88:91], v[170:173], v[210:213], v[88:91]
	v_mfma_f32_16x16x32_f16 v[80:83], v[178:181], v[210:213], v[80:83]
	v_mfma_f32_16x16x32_f16 v[72:75], v[170:173], v[218:221], v[72:75]
	v_mfma_f32_16x16x32_f16 v[68:71], v[178:181], v[218:221], v[68:71]
	s_nop 0
	s_barrier
; #define G_STAGE(bufoff, gbase, voff) do { _Pragma("unroll") for (int _i = 0; _i < 2; ++_i) \
;         __builtin_amdgcn_global_load_lds((const unsigned*)((const char*)(gbase) + (voff)[_i]), (LAS unsigned*)(lds + (bufoff) + ldsw + _i * 8192), 16, 0, 0); } while (0)
; #define G_LDA(dst, b, h) do { _Pragma("unroll") for (int m = 0; m < 4; ++m) { const i32x4 _p0 = *(const LAS i32x4*)(lds + G_SA(b, h) + aoff + m * 2048), _p1 = *(const LAS i32x4*)(lds + G_SA(b, h) + aoff + m * 2048 + 1024); \
;         dst[m] = __builtin_shufflevector(_p0, _p1, 0, 1, 2, 3, 4, 5, 6, 7); } } while (0)
; #define G_WAIT_V(n) asm volatile("s_waitcnt vmcnt(" #n ")" ::: "memory")
; #define G_WAIT_L(n) asm volatile("s_waitcnt lgkmcnt(" #n ")" ::: "memory")
; #define G_BAR __builtin_amdgcn_s_barrier()
; #define G_SCHED __builtin_amdgcn_sched_barrier(0)
; template <int NS, int MODE  , class Epi>
; __device__ __forceinline__ void gemm_phase(LAS unsigned char* lds, const Gemm g, const StaticOrder& S, const Epi& E) {
;     ...
;         for (int t = 0; t < NT; t += 2) {
;     ...
;             G_LDA(At, 1, 1); G_STAGE(G_SB(1, 0), b3, voffB); G_STAGE(G_SB(1, 1), b3 + hstep, voffB); G_STAGE(G_SA(1, 0), a3, voffA);
;             G_WAIT_V(8); G_WAIT_L(0); G_BAR; G_MMA(1, 0, At, B0); G_MMA(1, 1, At, B1); G_BAR; G_SCHED;
	s_add_i32 s25, s25, s2
	v_lshl_add_u64 v[182:183], s[76:77], 0, v[2:3]
	s_mov_b32 m0, s25
	ds_read_b128 v[190:193], v149 offset:49152
	ds_read_b128 v[194:197], v149 offset:50176
	ds_read_b128 v[198:201], v149 offset:51200
	ds_read_b128 v[202:205], v149 offset:52224
	ds_read_b128 v[206:209], v149 offset:53248
	ds_read_b128 v[210:213], v149 offset:54272
	ds_read_b128 v[214:217], v149 offset:55296
	ds_read_b128 v[218:221], v149 offset:56320
	global_load_lds_dwordx4 v[182:183], off
	s_add_i32 m0, s25, 0x2000
	s_add_u32 s30, s76, 0x80000
	v_lshl_add_u64 v[182:183], s[76:77], 0, v[132:133]
	s_addc_u32 s31, s77, 0
	s_add_i32 s25, s27, s2
	global_load_lds_dwordx4 v[182:183], off
	v_lshl_add_u64 v[182:183], s[30:31], 0, v[2:3]
	s_mov_b32 m0, s25
	s_nop 0
	global_load_lds_dwordx4 v[182:183], off
	v_lshl_add_u64 v[182:183], s[30:31], 0, v[132:133]
	s_add_i32 m0, s25, 0x2000
	s_nop 0
	global_load_lds_dwordx4 v[182:183], off
	v_lshl_add_u64 v[182:183], s[74:75], 0, v[136:137]
	s_mov_b32 m0, s35
	s_nop 0
	global_load_lds_dwordx4 v[182:183], off
	v_lshl_add_u64 v[182:183], s[74:75], 0, v[134:135]
	s_mov_b32 m0, s59
	s_nop 0
	global_load_lds_dwordx4 v[182:183], off
	s_waitcnt vmcnt(8)
	s_waitcnt lgkmcnt(0)
	s_nop 0
	s_waitcnt lgkmcnt(0)
	v_mfma_f32_16x16x32_f16 v[64:67], v[150:153], v[190:193], v[64:67]
	v_mfma_f32_16x16x32_f16 v[60:63], v[158:161], v[190:193], v[60:63]
	v_mfma_f32_16x16x32_f16 v[52:55], v[150:153], v[198:201], v[52:55]
	v_mfma_f32_16x16x32_f16 v[44:47], v[158:161], v[198:201], v[44:47]
	s_barrier
	v_mfma_f32_16x16x32_f16 v[36:39], v[150:153], v[206:209], v[36:39]
	v_mfma_f32_16x16x32_f16 v[28:31], v[158:161], v[206:209], v[28:31]
	v_mfma_f32_16x16x32_f16 v[20:23], v[150:153], v[214:217], v[20:23]
	v_mfma_f32_16x16x32_f16 v[12:15], v[158:161], v[214:217], v[12:15]
	v_mfma_f32_16x16x32_f16 v[64:67], v[154:157], v[194:197], v[64:67]
	v_mfma_f32_16x16x32_f16 v[60:63], v[162:165], v[194:197], v[60:63]
	v_mfma_f32_16x16x32_f16 v[52:55], v[154:157], v[202:205], v[52:55]
	v_mfma_f32_16x16x32_f16 v[44:47], v[162:165], v[202:205], v[44:47]
	v_mfma_f32_16x16x32_f16 v[36:39], v[154:157], v[210:213], v[36:39]
	v_mfma_f32_16x16x32_f16 v[28:31], v[162:165], v[210:213], v[28:31]
	v_mfma_f32_16x16x32_f16 v[20:23], v[154:157], v[218:221], v[20:23]
	v_mfma_f32_16x16x32_f16 v[12:15], v[162:165], v[218:221], v[12:15]
	s_nop 0
	s_nop 0
	v_mfma_f32_16x16x32_f16 v[56:59], v[166:169], v[190:193], v[56:59]
	v_mfma_f32_16x16x32_f16 v[48:51], v[174:177], v[190:193], v[48:51]
	v_mfma_f32_16x16x32_f16 v[40:43], v[166:169], v[198:201], v[40:43]
	v_mfma_f32_16x16x32_f16 v[32:35], v[174:177], v[198:201], v[32:35]
	v_mfma_f32_16x16x32_f16 v[24:27], v[166:169], v[206:209], v[24:27]
	v_mfma_f32_16x16x32_f16 v[16:19], v[174:177], v[206:209], v[16:19]
	v_mfma_f32_16x16x32_f16 v[8:11], v[166:169], v[214:217], v[8:11]
	v_mfma_f32_16x16x32_f16 v[4:7], v[174:177], v[214:217], v[4:7]
	v_mfma_f32_16x16x32_f16 v[56:59], v[170:173], v[194:197], v[56:59]
	v_mfma_f32_16x16x32_f16 v[48:51], v[178:181], v[194:197], v[48:51]
	v_mfma_f32_16x16x32_f16 v[40:43], v[170:173], v[202:205], v[40:43]
	v_mfma_f32_16x16x32_f16 v[32:35], v[178:181], v[202:205], v[32:35]
	v_mfma_f32_16x16x32_f16 v[24:27], v[170:173], v[210:213], v[24:27]
	v_mfma_f32_16x16x32_f16 v[16:19], v[178:181], v[210:213], v[16:19]
	v_mfma_f32_16x16x32_f16 v[8:11], v[170:173], v[218:221], v[8:11]
	v_mfma_f32_16x16x32_f16 v[4:7], v[178:181], v[218:221], v[4:7]
	s_nop 0
	s_barrier
	s_add_i32 s21, s21, 2
	s_add_u32 s72, s72, 0x100
	s_addc_u32 s73, s73, 0
	s_cmp_gt_u32 s21, 29
	s_cbranch_scc1 .LBB0_756

; #define G_STAGE(bufoff, gbase, voff) do { _Pragma("unroll") for (int _i = 0; _i < 2; ++_i) \
;         __builtin_amdgcn_global_load_lds((const unsigned*)((const char*)(gbase) + (voff)[_i]), (LAS unsigned*)(lds + (bufoff) + ldsw + _i * 8192), 16, 0, 0); } while (0)
; #define G_LDA(dst, b, h) do { _Pragma("unroll") for (int m = 0; m < 4; ++m) { const i32x4 _p0 = *(const LAS i32x4*)(lds + G_SA(b, h) + aoff + m * 2048), _p1 = *(const LAS i32x4*)(lds + G_SA(b, h) + aoff + m * 2048 + 1024); \
;         dst[m] = __builtin_shufflevector(_p0, _p1, 0, 1, 2, 3, 4, 5, 6, 7); } } while (0)
; #define G_LDB(dst, b, h) do { _Pragma("unroll") for (int n = 0; n < 2; ++n) { const i32x4 _p0 = *(const LAS i32x4*)(lds + G_SB(b, h) + boff + n * 2048), _p1 = *(const LAS i32x4*)(lds + G_SB(b, h) + boff + n * 2048 + 1024); \
;         dst[n] = __builtin_shufflevector(_p0, _p1, 0, 1, 2, 3, 4, 5, 6, 7); } } while (0)
; #define G_WAIT_V(n) asm volatile("s_waitcnt vmcnt(" #n ")" ::: "memory")
; #define G_WAIT_L(n) asm volatile("s_waitcnt lgkmcnt(" #n ")" ::: "memory")
; #define G_BAR __builtin_amdgcn_s_barrier()
; #define G_SCHED __builtin_amdgcn_sched_barrier(0)
; template <int NS, int MODE  , class Epi>
; __device__ __forceinline__ void gemm_phase(LAS unsigned char* lds, const Gemm g, const StaticOrder& S, const Epi& E) {
;     ...
;             G_LDB(B0, 0, 0); G_LDB(B1, 0, 1); G_SCHED; G_LDA(At, 0, 0); G_STAGE(G_SA(1, 1), a1 + hstep, voffA);
;             G_WAIT_V(8); G_WAIT_L(0); G_BAR; G_MMA(0, 0, At, B0); G_MMA(0, 1, At, B1); G_BAR; G_SCHED;
;             G_LDA(At, 0, 1); G_STAGE(G_SB(0, 0), b2, voffB); G_STAGE(G_SB(0, 1), b2 + hstep, voffB); G_STAGE(G_SA(0, 0), a2, voffA);
;             G_WAIT_V(8); G_WAIT_L(0); G_BAR; G_MMA(1, 0, At, B0); G_MMA(1, 1, At, B1); G_BAR; G_SCHED;
.LBB0_1126:
	s_add_i32 s21, 0, 0x10000
	s_add_i32 s30, 0, 0x14000
	v_add_u32_e32 v148, s21, v205
	v_add_u32_e32 v164, s30, v205
	ds_read_b128 v[136:139], v148
	ds_read_b128 v[140:143], v148 offset:1024
	ds_read_b128 v[144:147], v148 offset:2048
	ds_read_b128 v[148:151], v148 offset:3072
	ds_read_b128 v[152:155], v164
	ds_read_b128 v[156:159], v164 offset:1024
	ds_read_b128 v[160:163], v164 offset:2048
	ds_read_b128 v[164:167], v164 offset:3072
	v_lshl_add_u64 v[216:217], v[132:133], 0, s[60:61]
	s_add_i32 m0, s19, 0xc000
	ds_read_b128 v[176:179], v207
	ds_read_b128 v[180:183], v207 offset:1024
	ds_read_b128 v[188:191], v207 offset:2048
	ds_read_b128 v[192:195], v207 offset:3072
	ds_read_b128 v[196:199], v207 offset:4096
	ds_read_b128 v[200:203], v207 offset:5120
	ds_read_b128 v[208:211], v207 offset:6144
	ds_read_b128 v[212:215], v207 offset:7168
	global_load_lds_dwordx4 v[216:217], off
	v_lshl_add_u64 v[216:217], v[134:135], 0, s[60:61]
	s_add_i32 m0, s19, 0xe000
	s_nop 0
	global_load_lds_dwordx4 v[216:217], off
	s_waitcnt vmcnt(8)
	s_waitcnt lgkmcnt(0)
	s_nop 0
	s_waitcnt lgkmcnt(0)
	v_mfma_f32_16x16x32_f16 v[128:131], v[136:139], v[176:179], v[128:131]
	v_mfma_f32_16x16x32_f16 v[124:127], v[144:147], v[176:179], v[124:127]
	v_mfma_f32_16x16x32_f16 v[112:115], v[136:139], v[188:191], v[112:115]
	v_mfma_f32_16x16x32_f16 v[108:111], v[144:147], v[188:191], v[108:111]
	s_barrier
	v_mfma_f32_16x16x32_f16 v[100:103], v[136:139], v[196:199], v[100:103]
	v_mfma_f32_16x16x32_f16 v[92:95], v[144:147], v[196:199], v[92:95]
	v_mfma_f32_16x16x32_f16 v[88:91], v[136:139], v[208:211], v[88:91]
	v_mfma_f32_16x16x32_f16 v[80:83], v[144:147], v[208:211], v[80:83]
	v_mfma_f32_16x16x32_f16 v[128:131], v[140:143], v[180:183], v[128:131]
	v_mfma_f32_16x16x32_f16 v[124:127], v[148:151], v[180:183], v[124:127]
	v_mfma_f32_16x16x32_f16 v[112:115], v[140:143], v[192:195], v[112:115]
	v_mfma_f32_16x16x32_f16 v[108:111], v[148:151], v[192:195], v[108:111]
	v_mfma_f32_16x16x32_f16 v[100:103], v[140:143], v[200:203], v[100:103]
	v_mfma_f32_16x16x32_f16 v[92:95], v[148:151], v[200:203], v[92:95]
	v_mfma_f32_16x16x32_f16 v[88:91], v[140:143], v[212:215], v[88:91]
	v_mfma_f32_16x16x32_f16 v[80:83], v[148:151], v[212:215], v[80:83]
	s_nop 0
	s_nop 0
	v_mfma_f32_16x16x32_f16 v[120:123], v[152:155], v[176:179], v[120:123]
	v_mfma_f32_16x16x32_f16 v[116:119], v[160:163], v[176:179], v[116:119]
	v_mfma_f32_16x16x32_f16 v[104:107], v[152:155], v[188:191], v[104:107]
	v_mfma_f32_16x16x32_f16 v[96:99], v[160:163], v[188:191], v[96:99]
	v_mfma_f32_16x16x32_f16 v[84:87], v[152:155], v[196:199], v[84:87]
	v_mfma_f32_16x16x32_f16 v[76:79], v[160:163], v[196:199], v[76:79]
	v_mfma_f32_16x16x32_f16 v[72:75], v[152:155], v[208:211], v[72:75]
	v_mfma_f32_16x16x32_f16 v[68:71], v[160:163], v[208:211], v[68:71]
	v_mfma_f32_16x16x32_f16 v[120:123], v[156:159], v[180:183], v[120:123]
	v_mfma_f32_16x16x32_f16 v[116:119], v[164:167], v[180:183], v[116:119]
	v_mfma_f32_16x16x32_f16 v[104:107], v[156:159], v[192:195], v[104:107]
	v_mfma_f32_16x16x32_f16 v[96:99], v[164:167], v[192:195], v[96:99]
	v_mfma_f32_16x16x32_f16 v[84:87], v[156:159], v[200:203], v[84:87]
	v_mfma_f32_16x16x32_f16 v[76:79], v[164:167], v[200:203], v[76:79]
	v_mfma_f32_16x16x32_f16 v[72:75], v[156:159], v[212:215], v[72:75]
	v_mfma_f32_16x16x32_f16 v[68:71], v[164:167], v[212:215], v[68:71]
	s_nop 0
	s_barrier
	s_add_i32 s21, s21, s18
	v_lshl_add_u64 v[216:217], s[68:69], 0, v[2:3]
	s_mov_b32 m0, s21
	ds_read_b128 v[176:179], v207 offset:16384
	ds_read_b128 v[180:183], v207 offset:17408
	ds_read_b128 v[188:191], v207 offset:18432
	ds_read_b128 v[192:195], v207 offset:19456
	ds_read_b128 v[196:199], v207 offset:20480
	ds_read_b128 v[200:203], v207 offset:21504
	ds_read_b128 v[208:211], v207 offset:22528
	ds_read_b128 v[212:215], v207 offset:23552
	global_load_lds_dwordx4 v[216:217], off
	s_add_i32 m0, s21, 0x2000
	s_add_u32 s24, s68, 0x80000
	v_lshl_add_u64 v[216:217], s[68:69], 0, v[168:169]
	s_addc_u32 s25, s69, 0
	s_add_i32 s21, s30, s18
	global_load_lds_dwordx4 v[216:217], off
	v_lshl_add_u64 v[216:217], s[24:25], 0, v[2:3]
	s_mov_b32 m0, s21
	s_nop 0
	global_load_lds_dwordx4 v[216:217], off
	v_lshl_add_u64 v[216:217], s[24:25], 0, v[168:169]
	s_add_i32 m0, s21, 0x2000
	s_nop 0
	global_load_lds_dwordx4 v[216:217], off
	v_lshl_add_u64 v[216:217], s[66:67], 0, v[172:173]
	s_mov_b32 m0, s19
	s_nop 0
	global_load_lds_dwordx4 v[216:217], off
	v_lshl_add_u64 v[216:217], s[66:67], 0, v[170:171]
	s_mov_b32 m0, s29
	s_nop 0
	global_load_lds_dwordx4 v[216:217], off
	s_waitcnt vmcnt(8)
	s_waitcnt lgkmcnt(0)
	s_nop 0
	s_waitcnt lgkmcnt(0)
	v_mfma_f32_16x16x32_f16 v[64:67], v[136:139], v[176:179], v[64:67]
	v_mfma_f32_16x16x32_f16 v[60:63], v[144:147], v[176:179], v[60:63]
	v_mfma_f32_16x16x32_f16 v[52:55], v[136:139], v[188:191], v[52:55]
	v_mfma_f32_16x16x32_f16 v[44:47], v[144:147], v[188:191], v[44:47]
	s_barrier
; #define G_STAGE(bufoff, gbase, voff) do { _Pragma("unroll") for (int _i = 0; _i < 2; ++_i) \
;         __builtin_amdgcn_global_load_lds((const unsigned*)((const char*)(gbase) + (voff)[_i]), (LAS unsigned*)(lds + (bufoff) + ldsw + _i * 8192), 16, 0, 0); } while (0)
; #define G_LDA(dst, b, h) do { _Pragma("unroll") for (int m = 0; m < 4; ++m) { const i32x4 _p0 = *(const LAS i32x4*)(lds + G_SA(b, h) + aoff + m * 2048), _p1 = *(const LAS i32x4*)(lds + G_SA(b, h) + aoff + m * 2048 + 1024); \
;         dst[m] = __builtin_shufflevector(_p0, _p1, 0, 1, 2, 3, 4, 5, 6, 7); } } while (0)
; #define G_LDB(dst, b, h) do { _Pragma("unroll") for (int n = 0; n < 2; ++n) { const i32x4 _p0 = *(const LAS i32x4*)(lds + G_SB(b, h) + boff + n * 2048), _p1 = *(const LAS i32x4*)(lds + G_SB(b, h) + boff + n * 2048 + 1024); \
;         dst[n] = __builtin_shufflevector(_p0, _p1, 0, 1, 2, 3, 4, 5, 6, 7); } } while (0)
; #define G_WAIT_V(n) asm volatile("s_waitcnt vmcnt(" #n ")" ::: "memory")
; #define G_WAIT_L(n) asm volatile("s_waitcnt lgkmcnt(" #n ")" ::: "memory")
; #define G_BAR __builtin_amdgcn_s_barrier()
; #define G_SCHED __builtin_amdgcn_sched_barrier(0)
; template <int NS, int MODE  , class Epi>
; __device__ __forceinline__ void gemm_phase(LAS unsigned char* lds, const Gemm g, const StaticOrder& S, const Epi& E) {
;     ...
;             G_WAIT_V(8); G_WAIT_L(0); G_BAR; G_MMA(1, 0, At, B0); G_MMA(1, 1, At, B1); G_BAR; G_SCHED;
;             G_LDB(B0, 1, 0); G_LDB(B1, 1, 1); G_SCHED; G_LDA(At, 1, 0); G_STAGE(G_SA(0, 1), a2 + hstep, voffA);
;             G_WAIT_V(8); G_WAIT_L(0); G_BAR; G_MMA(0, 0, At, B0); G_MMA(0, 1, At, B1); G_BAR; G_SCHED;
	v_mfma_f32_16x16x32_f16 v[36:39], v[136:139], v[196:199], v[36:39]
	v_mfma_f32_16x16x32_f16 v[28:31], v[144:147], v[196:199], v[28:31]
	v_mfma_f32_16x16x32_f16 v[20:23], v[136:139], v[208:211], v[20:23]
	v_mfma_f32_16x16x32_f16 v[12:15], v[144:147], v[208:211], v[12:15]
	v_mfma_f32_16x16x32_f16 v[64:67], v[140:143], v[180:183], v[64:67]
	v_mfma_f32_16x16x32_f16 v[60:63], v[148:151], v[180:183], v[60:63]
	v_mfma_f32_16x16x32_f16 v[52:55], v[140:143], v[192:195], v[52:55]
	v_mfma_f32_16x16x32_f16 v[44:47], v[148:151], v[192:195], v[44:47]
	v_mfma_f32_16x16x32_f16 v[36:39], v[140:143], v[200:203], v[36:39]
	v_mfma_f32_16x16x32_f16 v[28:31], v[148:151], v[200:203], v[28:31]
	v_mfma_f32_16x16x32_f16 v[20:23], v[140:143], v[212:215], v[20:23]
	v_mfma_f32_16x16x32_f16 v[12:15], v[148:151], v[212:215], v[12:15]
	s_nop 0
	s_nop 0
	v_mfma_f32_16x16x32_f16 v[56:59], v[152:155], v[176:179], v[56:59]
	v_mfma_f32_16x16x32_f16 v[48:51], v[160:163], v[176:179], v[48:51]
	v_mfma_f32_16x16x32_f16 v[40:43], v[152:155], v[188:191], v[40:43]
	v_mfma_f32_16x16x32_f16 v[32:35], v[160:163], v[188:191], v[32:35]
	v_mfma_f32_16x16x32_f16 v[24:27], v[152:155], v[196:199], v[24:27]
	v_mfma_f32_16x16x32_f16 v[16:19], v[160:163], v[196:199], v[16:19]
	v_mfma_f32_16x16x32_f16 v[8:11], v[152:155], v[208:211], v[8:11]
	v_mfma_f32_16x16x32_f16 v[4:7], v[160:163], v[208:211], v[4:7]
	v_mfma_f32_16x16x32_f16 v[56:59], v[156:159], v[180:183], v[56:59]
	v_mfma_f32_16x16x32_f16 v[48:51], v[164:167], v[180:183], v[48:51]
	v_mfma_f32_16x16x32_f16 v[40:43], v[156:159], v[192:195], v[40:43]
	v_mfma_f32_16x16x32_f16 v[32:35], v[164:167], v[192:195], v[32:35]
	v_mfma_f32_16x16x32_f16 v[24:27], v[156:159], v[200:203], v[24:27]
	v_mfma_f32_16x16x32_f16 v[16:19], v[164:167], v[200:203], v[16:19]
	v_mfma_f32_16x16x32_f16 v[8:11], v[156:159], v[212:215], v[8:11]
	v_mfma_f32_16x16x32_f16 v[4:7], v[164:167], v[212:215], v[4:7]
	s_nop 0
	s_barrier
	s_add_i32 s21, 0, 0x18000
	s_add_i32 s30, 0, 0x1c000
	v_add_u32_e32 v148, s21, v205
	v_add_u32_e32 v164, s30, v205
	ds_read_b128 v[136:139], v148
	ds_read_b128 v[140:143], v148 offset:1024
	ds_read_b128 v[144:147], v148 offset:2048
	ds_read_b128 v[148:151], v148 offset:3072
	ds_read_b128 v[152:155], v164
	ds_read_b128 v[156:159], v164 offset:1024
	ds_read_b128 v[160:163], v164 offset:2048
	ds_read_b128 v[164:167], v164 offset:3072
	s_add_u32 s24, s66, 0x80000
	s_addc_u32 s25, s67, 0
	s_mov_b32 m0, s56
	v_lshl_add_u64 v[216:217], s[24:25], 0, v[172:173]
	ds_read_b128 v[176:179], v207 offset:32768
	ds_read_b128 v[180:183], v207 offset:33792
	ds_read_b128 v[188:191], v207 offset:34816
	ds_read_b128 v[192:195], v207 offset:35840
	ds_read_b128 v[196:199], v207 offset:36864
	ds_read_b128 v[200:203], v207 offset:37888
	ds_read_b128 v[208:211], v207 offset:38912
	ds_read_b128 v[212:215], v207 offset:39936
	global_load_lds_dwordx4 v[216:217], off
	v_lshl_add_u64 v[216:217], s[24:25], 0, v[170:171]
	s_mov_b32 m0, s70
	s_nop 0
	global_load_lds_dwordx4 v[216:217], off
	s_waitcnt vmcnt(8)
	s_waitcnt lgkmcnt(0)
	s_nop 0
	s_waitcnt lgkmcnt(0)
	v_mfma_f32_16x16x32_f16 v[128:131], v[136:139], v[176:179], v[128:131]
	v_mfma_f32_16x16x32_f16 v[124:127], v[144:147], v[176:179], v[124:127]
	v_mfma_f32_16x16x32_f16 v[112:115], v[136:139], v[188:191], v[112:115]
	v_mfma_f32_16x16x32_f16 v[108:111], v[144:147], v[188:191], v[108:111]
	s_barrier
	v_mfma_f32_16x16x32_f16 v[100:103], v[136:139], v[196:199], v[100:103]
	v_mfma_f32_16x16x32_f16 v[92:95], v[144:147], v[196:199], v[92:95]
	v_mfma_f32_16x16x32_f16 v[88:91], v[136:139], v[208:211], v[88:91]
	v_mfma_f32_16x16x32_f16 v[80:83], v[144:147], v[208:211], v[80:83]
	v_mfma_f32_16x16x32_f16 v[128:131], v[140:143], v[180:183], v[128:131]
	v_mfma_f32_16x16x32_f16 v[124:127], v[148:151], v[180:183], v[124:127]
	v_mfma_f32_16x16x32_f16 v[112:115], v[140:143], v[192:195], v[112:115]
	v_mfma_f32_16x16x32_f16 v[108:111], v[148:151], v[192:195], v[108:111]
	v_mfma_f32_16x16x32_f16 v[100:103], v[140:143], v[200:203], v[100:103]
	v_mfma_f32_16x16x32_f16 v[92:95], v[148:151], v[200:203], v[92:95]
	v_mfma_f32_16x16x32_f16 v[88:91], v[140:143], v[212:215], v[88:91]
	v_mfma_f32_16x16x32_f16 v[80:83], v[148:151], v[212:215], v[80:83]
	s_nop 0
	s_nop 0
	v_mfma_f32_16x16x32_f16 v[120:123], v[152:155], v[176:179], v[120:123]
	v_mfma_f32_16x16x32_f16 v[116:119], v[160:163], v[176:179], v[116:119]
	v_mfma_f32_16x16x32_f16 v[104:107], v[152:155], v[188:191], v[104:107]
	v_mfma_f32_16x16x32_f16 v[96:99], v[160:163], v[188:191], v[96:99]
	v_mfma_f32_16x16x32_f16 v[84:87], v[152:155], v[196:199], v[84:87]
	v_mfma_f32_16x16x32_f16 v[76:79], v[160:163], v[196:199], v[76:79]
	v_mfma_f32_16x16x32_f16 v[72:75], v[152:155], v[208:211], v[72:75]
	v_mfma_f32_16x16x32_f16 v[68:71], v[160:163], v[208:211], v[68:71]
	v_mfma_f32_16x16x32_f16 v[120:123], v[156:159], v[180:183], v[120:123]
	v_mfma_f32_16x16x32_f16 v[116:119], v[164:167], v[180:183], v[116:119]
	v_mfma_f32_16x16x32_f16 v[104:107], v[156:159], v[192:195], v[104:107]
	v_mfma_f32_16x16x32_f16 v[96:99], v[164:167], v[192:195], v[96:99]
	v_mfma_f32_16x16x32_f16 v[84:87], v[156:159], v[200:203], v[84:87]
	v_mfma_f32_16x16x32_f16 v[76:79], v[164:167], v[200:203], v[76:79]
	v_mfma_f32_16x16x32_f16 v[72:75], v[156:159], v[212:215], v[72:75]
	v_mfma_f32_16x16x32_f16 v[68:71], v[164:167], v[212:215], v[68:71]
	s_nop 0
	s_barrier
; #define G_STAGE(bufoff, gbase, voff) do { _Pragma("unroll") for (int _i = 0; _i < 2; ++_i) \
;         __builtin_amdgcn_global_load_lds((const unsigned*)((const char*)(gbase) + (voff)[_i]), (LAS unsigned*)(lds + (bufoff) + ldsw + _i * 8192), 16, 0, 0); } while (0)
; #define G_LDA(dst, b, h) do { _Pragma("unroll") for (int m = 0; m < 4; ++m) { const i32x4 _p0 = *(const LAS i32x4*)(lds + G_SA(b, h) + aoff + m * 2048), _p1 = *(const LAS i32x4*)(lds + G_SA(b, h) + aoff + m * 2048 + 1024); \
;         dst[m] = __builtin_shufflevector(_p0, _p1, 0, 1, 2, 3, 4, 5, 6, 7); } } while (0)
; #define G_WAIT_V(n) asm volatile("s_waitcnt vmcnt(" #n ")" ::: "memory")
; #define G_WAIT_L(n) asm volatile("s_waitcnt lgkmcnt(" #n ")" ::: "memory")
; #define G_BAR __builtin_amdgcn_s_barrier()
; #define G_SCHED __builtin_amdgcn_sched_barrier(0)
; template <int NS, int MODE  , class Epi>
; __device__ __forceinline__ void gemm_phase(LAS unsigned char* lds, const Gemm g, const StaticOrder& S, const Epi& E) {
;     ...
;         for (int t = 0; t < NT; t += 2) {
;     ...
;             G_LDA(At, 1, 1); G_STAGE(G_SB(1, 0), b3, voffB); G_STAGE(G_SB(1, 1), b3 + hstep, voffB); G_STAGE(G_SA(1, 0), a3, voffA);
;             G_WAIT_V(8); G_WAIT_L(0); G_BAR; G_MMA(1, 0, At, B0); G_MMA(1, 1, At, B1); G_BAR; G_SCHED;
	s_add_i32 s21, s21, s18
	v_lshl_add_u64 v[216:217], s[64:65], 0, v[2:3]
	s_mov_b32 m0, s21
	ds_read_b128 v[176:179], v207 offset:49152
	ds_read_b128 v[180:183], v207 offset:50176
	ds_read_b128 v[188:191], v207 offset:51200
	ds_read_b128 v[192:195], v207 offset:52224
	ds_read_b128 v[196:199], v207 offset:53248
	ds_read_b128 v[200:203], v207 offset:54272
	ds_read_b128 v[208:211], v207 offset:55296
	ds_read_b128 v[212:215], v207 offset:56320
	global_load_lds_dwordx4 v[216:217], off
	s_add_i32 m0, s21, 0x2000
	s_add_u32 s24, s64, 0x80000
	v_lshl_add_u64 v[216:217], s[64:65], 0, v[168:169]
	s_addc_u32 s25, s65, 0
	s_add_i32 s21, s30, s18
	global_load_lds_dwordx4 v[216:217], off
	v_lshl_add_u64 v[216:217], s[24:25], 0, v[2:3]
	s_mov_b32 m0, s21
	s_nop 0
	global_load_lds_dwordx4 v[216:217], off
	v_lshl_add_u64 v[216:217], s[24:25], 0, v[168:169]
	s_add_i32 m0, s21, 0x2000
	s_nop 0
	global_load_lds_dwordx4 v[216:217], off
	v_lshl_add_u64 v[216:217], s[62:63], 0, v[172:173]
	s_mov_b32 m0, s73
	s_nop 0
	global_load_lds_dwordx4 v[216:217], off
	v_lshl_add_u64 v[216:217], s[62:63], 0, v[170:171]
	s_mov_b32 m0, s74
	s_nop 0
	global_load_lds_dwordx4 v[216:217], off
	s_waitcnt vmcnt(8)
	s_waitcnt lgkmcnt(0)
	s_nop 0
	s_waitcnt lgkmcnt(0)
	v_mfma_f32_16x16x32_f16 v[64:67], v[136:139], v[176:179], v[64:67]
	v_mfma_f32_16x16x32_f16 v[60:63], v[144:147], v[176:179], v[60:63]
	v_mfma_f32_16x16x32_f16 v[52:55], v[136:139], v[188:191], v[52:55]
	v_mfma_f32_16x16x32_f16 v[44:47], v[144:147], v[188:191], v[44:47]
	s_barrier
	v_mfma_f32_16x16x32_f16 v[36:39], v[136:139], v[196:199], v[36:39]
	v_mfma_f32_16x16x32_f16 v[28:31], v[144:147], v[196:199], v[28:31]
	v_mfma_f32_16x16x32_f16 v[20:23], v[136:139], v[208:211], v[20:23]
	v_mfma_f32_16x16x32_f16 v[12:15], v[144:147], v[208:211], v[12:15]
	v_mfma_f32_16x16x32_f16 v[64:67], v[140:143], v[180:183], v[64:67]
	v_mfma_f32_16x16x32_f16 v[60:63], v[148:151], v[180:183], v[60:63]
	v_mfma_f32_16x16x32_f16 v[52:55], v[140:143], v[192:195], v[52:55]
	v_mfma_f32_16x16x32_f16 v[44:47], v[148:151], v[192:195], v[44:47]
	v_mfma_f32_16x16x32_f16 v[36:39], v[140:143], v[200:203], v[36:39]
	v_mfma_f32_16x16x32_f16 v[28:31], v[148:151], v[200:203], v[28:31]
	v_mfma_f32_16x16x32_f16 v[20:23], v[140:143], v[212:215], v[20:23]
	v_mfma_f32_16x16x32_f16 v[12:15], v[148:151], v[212:215], v[12:15]
	s_nop 0
	s_nop 0
	v_mfma_f32_16x16x32_f16 v[56:59], v[152:155], v[176:179], v[56:59]
	v_mfma_f32_16x16x32_f16 v[48:51], v[160:163], v[176:179], v[48:51]
	v_mfma_f32_16x16x32_f16 v[40:43], v[152:155], v[188:191], v[40:43]
	v_mfma_f32_16x16x32_f16 v[32:35], v[160:163], v[188:191], v[32:35]
	v_mfma_f32_16x16x32_f16 v[24:27], v[152:155], v[196:199], v[24:27]
	v_mfma_f32_16x16x32_f16 v[16:19], v[160:163], v[196:199], v[16:19]
	v_mfma_f32_16x16x32_f16 v[8:11], v[152:155], v[208:211], v[8:11]
	v_mfma_f32_16x16x32_f16 v[4:7], v[160:163], v[208:211], v[4:7]
	v_mfma_f32_16x16x32_f16 v[56:59], v[156:159], v[180:183], v[56:59]
	v_mfma_f32_16x16x32_f16 v[48:51], v[164:167], v[180:183], v[48:51]
	v_mfma_f32_16x16x32_f16 v[40:43], v[156:159], v[192:195], v[40:43]
	v_mfma_f32_16x16x32_f16 v[32:35], v[164:167], v[192:195], v[32:35]
	v_mfma_f32_16x16x32_f16 v[24:27], v[156:159], v[200:203], v[24:27]
	v_mfma_f32_16x16x32_f16 v[16:19], v[164:167], v[200:203], v[16:19]
	v_mfma_f32_16x16x32_f16 v[8:11], v[156:159], v[212:215], v[8:11]
	v_mfma_f32_16x16x32_f16 v[4:7], v[164:167], v[212:215], v[4:7]
	s_nop 0
	s_barrier
	s_add_u32 s60, s60, 0x100
	s_addc_u32 s61, s61, 0
	s_add_i32 s13, s13, 2
	s_cmp_gt_u32 s13, 29
	s_cbranch_scc1 .LBB0_1129

; #define G_STAGE(bufoff, gbase, voff) do { _Pragma("unroll") for (int _i = 0; _i < 2; ++_i) \
;         __builtin_amdgcn_global_load_lds((const unsigned*)((const char*)(gbase) + (voff)[_i]), (LAS unsigned*)(lds + (bufoff) + ldsw + _i * 8192), 16, 0, 0); } while (0)
; #define G_LDA(dst, b, h) do { _Pragma("unroll") for (int m = 0; m < 4; ++m) { const i32x4 _p0 = *(const LAS i32x4*)(lds + G_SA(b, h) + aoff + m * 2048), _p1 = *(const LAS i32x4*)(lds + G_SA(b, h) + aoff + m * 2048 + 1024); \
;         dst[m] = __builtin_shufflevector(_p0, _p1, 0, 1, 2, 3, 4, 5, 6, 7); } } while (0)
; #define G_LDB(dst, b, h) do { _Pragma("unroll") for (int n = 0; n < 2; ++n) { const i32x4 _p0 = *(const LAS i32x4*)(lds + G_SB(b, h) + boff + n * 2048), _p1 = *(const LAS i32x4*)(lds + G_SB(b, h) + boff + n * 2048 + 1024); \
;         dst[n] = __builtin_shufflevector(_p0, _p1, 0, 1, 2, 3, 4, 5, 6, 7); } } while (0)
; #define G_WAIT_V(n) asm volatile("s_waitcnt vmcnt(" #n ")" ::: "memory")
; #define G_WAIT_L(n) asm volatile("s_waitcnt lgkmcnt(" #n ")" ::: "memory")
; #define G_BAR __builtin_amdgcn_s_barrier()
; #define G_SCHED __builtin_amdgcn_sched_barrier(0)
; template <int NS, int MODE  , class Epi>
; __device__ __forceinline__ void gemm_phase(LAS unsigned char* lds, const Gemm g, const StaticOrder& S, const Epi& E) {
;     ...
;             G_LDB(B0, 0, 0); G_LDB(B1, 0, 1); G_SCHED; G_LDA(At, 0, 0); G_STAGE(G_SA(1, 1), a1 + hstep, voffA);
;             G_WAIT_V(8); G_WAIT_L(0); G_BAR; G_MMA(0, 0, At, B0); G_MMA(0, 1, At, B1); G_BAR; G_SCHED;
;             G_LDA(At, 0, 1); G_STAGE(G_SB(0, 0), b2, voffB); G_STAGE(G_SB(0, 1), b2 + hstep, voffB); G_STAGE(G_SA(0, 0), a2, voffA);
;             G_WAIT_V(8); G_WAIT_L(0); G_BAR; G_MMA(1, 0, At, B0); G_MMA(1, 1, At, B1); G_BAR; G_SCHED;
.LBB0_1276:
	s_add_i32 s21, 0, 0x10000
	s_add_i32 s30, 0, 0x14000
	v_add_u32_e32 v132, s21, v190
	v_add_u32_e32 v136, s30, v190
	ds_read_b128 v[160:163], v132
	ds_read_b128 v[148:151], v132 offset:1024
	ds_read_b128 v[156:159], v132 offset:2048
	ds_read_b128 v[152:155], v132 offset:3072
	ds_read_b128 v[144:147], v136
	ds_read_b128 v[132:135], v136 offset:1024
	ds_read_b128 v[140:143], v136 offset:2048
	ds_read_b128 v[136:139], v136 offset:3072
	v_lshl_add_u64 v[226:227], v[174:175], 0, s[60:61]
	s_add_i32 m0, s19, 0xc000
	ds_read_b128 v[176:179], v194
	ds_read_b128 v[180:183], v194 offset:1024
	ds_read_b128 v[202:205], v194 offset:2048
	ds_read_b128 v[206:209], v194 offset:3072
	ds_read_b128 v[210:213], v194 offset:4096
	ds_read_b128 v[214:217], v194 offset:5120
	ds_read_b128 v[218:221], v194 offset:6144
	ds_read_b128 v[222:225], v194 offset:7168
	global_load_lds_dwordx4 v[226:227], off
	v_lshl_add_u64 v[226:227], v[186:187], 0, s[60:61]
	s_add_i32 m0, s19, 0xe000
	s_nop 0
	global_load_lds_dwordx4 v[226:227], off
	s_waitcnt vmcnt(8)
	s_waitcnt lgkmcnt(0)
	s_nop 0
	s_waitcnt lgkmcnt(0)
	v_mfma_i32_16x16x64_i8 v[128:131], v[160:163], v[176:179], v[128:131]
	v_mfma_i32_16x16x64_i8 v[120:123], v[156:159], v[176:179], v[120:123]
	v_mfma_i32_16x16x64_i8 v[112:115], v[160:163], v[202:205], v[112:115]
	v_mfma_i32_16x16x64_i8 v[104:107], v[156:159], v[202:205], v[104:107]
	s_barrier
	v_mfma_i32_16x16x64_i8 v[96:99], v[160:163], v[210:213], v[96:99]
	v_mfma_i32_16x16x64_i8 v[88:91], v[156:159], v[210:213], v[88:91]
	v_mfma_i32_16x16x64_i8 v[80:83], v[160:163], v[218:221], v[80:83]
	v_mfma_i32_16x16x64_i8 v[72:75], v[156:159], v[218:221], v[72:75]
	s_nop 0
	v_mfma_i32_16x16x64_i8 v[128:131], v[148:151], v[180:183], v[128:131]
	v_mfma_i32_16x16x64_i8 v[120:123], v[152:155], v[180:183], v[120:123]
	v_mfma_i32_16x16x64_i8 v[112:115], v[148:151], v[206:209], v[112:115]
	v_mfma_i32_16x16x64_i8 v[104:107], v[152:155], v[206:209], v[104:107]
	v_mfma_i32_16x16x64_i8 v[96:99], v[148:151], v[214:217], v[96:99]
	v_mfma_i32_16x16x64_i8 v[88:91], v[152:155], v[214:217], v[88:91]
	v_mfma_i32_16x16x64_i8 v[80:83], v[148:151], v[222:225], v[80:83]
	v_mfma_i32_16x16x64_i8 v[72:75], v[152:155], v[222:225], v[72:75]
	s_nop 0
	s_nop 0
	v_mfma_i32_16x16x64_i8 v[124:127], v[144:147], v[176:179], v[124:127]
	v_mfma_i32_16x16x64_i8 v[116:119], v[140:143], v[176:179], v[116:119]
	v_mfma_i32_16x16x64_i8 v[108:111], v[144:147], v[202:205], v[108:111]
	v_mfma_i32_16x16x64_i8 v[100:103], v[140:143], v[202:205], v[100:103]
	v_mfma_i32_16x16x64_i8 v[92:95], v[144:147], v[210:213], v[92:95]
	v_mfma_i32_16x16x64_i8 v[84:87], v[140:143], v[210:213], v[84:87]
	v_mfma_i32_16x16x64_i8 v[76:79], v[144:147], v[218:221], v[76:79]
	v_mfma_i32_16x16x64_i8 v[68:71], v[140:143], v[218:221], v[68:71]
	s_nop 0
	v_mfma_i32_16x16x64_i8 v[124:127], v[132:135], v[180:183], v[124:127]
	v_mfma_i32_16x16x64_i8 v[116:119], v[136:139], v[180:183], v[116:119]
	v_mfma_i32_16x16x64_i8 v[108:111], v[132:135], v[206:209], v[108:111]
	v_mfma_i32_16x16x64_i8 v[100:103], v[136:139], v[206:209], v[100:103]
	v_mfma_i32_16x16x64_i8 v[92:95], v[132:135], v[214:217], v[92:95]
	v_mfma_i32_16x16x64_i8 v[84:87], v[136:139], v[214:217], v[84:87]
	v_mfma_i32_16x16x64_i8 v[76:79], v[132:135], v[222:225], v[76:79]
	v_mfma_i32_16x16x64_i8 v[68:71], v[136:139], v[222:225], v[68:71]
	s_nop 0
	s_barrier
	s_add_i32 s21, s21, s18
	v_lshl_add_u64 v[226:227], s[68:69], 0, v[2:3]
	s_mov_b32 m0, s21
	ds_read_b128 v[176:179], v194 offset:16384
	ds_read_b128 v[180:183], v194 offset:17408
	ds_read_b128 v[202:205], v194 offset:18432
	ds_read_b128 v[206:209], v194 offset:19456
	ds_read_b128 v[210:213], v194 offset:20480
	ds_read_b128 v[214:217], v194 offset:21504
	ds_read_b128 v[218:221], v194 offset:22528
	ds_read_b128 v[222:225], v194 offset:23552
	global_load_lds_dwordx4 v[226:227], off
	s_add_i32 m0, s21, 0x2000
	s_add_u32 s24, s68, 0x40000
	v_lshl_add_u64 v[226:227], s[68:69], 0, v[164:165]
	s_addc_u32 s25, s69, 0
	s_add_i32 s21, s30, s18
	global_load_lds_dwordx4 v[226:227], off
	v_lshl_add_u64 v[226:227], s[24:25], 0, v[2:3]
	s_mov_b32 m0, s21
	s_nop 0
	global_load_lds_dwordx4 v[226:227], off
	v_lshl_add_u64 v[226:227], s[24:25], 0, v[164:165]
	s_add_i32 m0, s21, 0x2000
	s_nop 0
	global_load_lds_dwordx4 v[226:227], off
	v_lshl_add_u64 v[226:227], s[66:67], 0, v[168:169]
	s_mov_b32 m0, s19
	s_nop 0
	global_load_lds_dwordx4 v[226:227], off
	v_lshl_add_u64 v[226:227], s[66:67], 0, v[166:167]
	s_mov_b32 m0, s29
	s_nop 0
	global_load_lds_dwordx4 v[226:227], off
	s_waitcnt vmcnt(8)
	s_waitcnt lgkmcnt(0)
	s_nop 0
	s_waitcnt lgkmcnt(0)
	v_mfma_i32_16x16x64_i8 v[64:67], v[160:163], v[176:179], v[64:67]
	v_mfma_i32_16x16x64_i8 v[56:59], v[156:159], v[176:179], v[56:59]
	v_mfma_i32_16x16x64_i8 v[48:51], v[160:163], v[202:205], v[48:51]
	v_mfma_i32_16x16x64_i8 v[40:43], v[156:159], v[202:205], v[40:43]
	s_barrier
; #define G_STAGE(bufoff, gbase, voff) do { _Pragma("unroll") for (int _i = 0; _i < 2; ++_i) \
;         __builtin_amdgcn_global_load_lds((const unsigned*)((const char*)(gbase) + (voff)[_i]), (LAS unsigned*)(lds + (bufoff) + ldsw + _i * 8192), 16, 0, 0); } while (0)
; #define G_LDA(dst, b, h) do { _Pragma("unroll") for (int m = 0; m < 4; ++m) { const i32x4 _p0 = *(const LAS i32x4*)(lds + G_SA(b, h) + aoff + m * 2048), _p1 = *(const LAS i32x4*)(lds + G_SA(b, h) + aoff + m * 2048 + 1024); \
;         dst[m] = __builtin_shufflevector(_p0, _p1, 0, 1, 2, 3, 4, 5, 6, 7); } } while (0)
; #define G_LDB(dst, b, h) do { _Pragma("unroll") for (int n = 0; n < 2; ++n) { const i32x4 _p0 = *(const LAS i32x4*)(lds + G_SB(b, h) + boff + n * 2048), _p1 = *(const LAS i32x4*)(lds + G_SB(b, h) + boff + n * 2048 + 1024); \
;         dst[n] = __builtin_shufflevector(_p0, _p1, 0, 1, 2, 3, 4, 5, 6, 7); } } while (0)
; #define G_WAIT_V(n) asm volatile("s_waitcnt vmcnt(" #n ")" ::: "memory")
; #define G_WAIT_L(n) asm volatile("s_waitcnt lgkmcnt(" #n ")" ::: "memory")
; #define G_BAR __builtin_amdgcn_s_barrier()
; #define G_SCHED __builtin_amdgcn_sched_barrier(0)
; template <int NS, int MODE  , class Epi>
; __device__ __forceinline__ void gemm_phase(LAS unsigned char* lds, const Gemm g, const StaticOrder& S, const Epi& E) {
;     ...
;             G_WAIT_V(8); G_WAIT_L(0); G_BAR; G_MMA(1, 0, At, B0); G_MMA(1, 1, At, B1); G_BAR; G_SCHED;
;             G_LDB(B0, 1, 0); G_LDB(B1, 1, 1); G_SCHED; G_LDA(At, 1, 0); G_STAGE(G_SA(0, 1), a2 + hstep, voffA);
;             G_WAIT_V(8); G_WAIT_L(0); G_BAR; G_MMA(0, 0, At, B0); G_MMA(0, 1, At, B1); G_BAR; G_SCHED;
	v_mfma_i32_16x16x64_i8 v[32:35], v[160:163], v[210:213], v[32:35]
	v_mfma_i32_16x16x64_i8 v[24:27], v[156:159], v[210:213], v[24:27]
	v_mfma_i32_16x16x64_i8 v[16:19], v[160:163], v[218:221], v[16:19]
	v_mfma_i32_16x16x64_i8 v[8:11], v[156:159], v[218:221], v[8:11]
	s_nop 0
	v_mfma_i32_16x16x64_i8 v[64:67], v[148:151], v[180:183], v[64:67]
	v_mfma_i32_16x16x64_i8 v[56:59], v[152:155], v[180:183], v[56:59]
	v_mfma_i32_16x16x64_i8 v[48:51], v[148:151], v[206:209], v[48:51]
	v_mfma_i32_16x16x64_i8 v[40:43], v[152:155], v[206:209], v[40:43]
	v_mfma_i32_16x16x64_i8 v[32:35], v[148:151], v[214:217], v[32:35]
	v_mfma_i32_16x16x64_i8 v[24:27], v[152:155], v[214:217], v[24:27]
	v_mfma_i32_16x16x64_i8 v[16:19], v[148:151], v[222:225], v[16:19]
	v_mfma_i32_16x16x64_i8 v[8:11], v[152:155], v[222:225], v[8:11]
	s_nop 0
	s_nop 0
	v_mfma_i32_16x16x64_i8 v[60:63], v[144:147], v[176:179], v[60:63]
	v_mfma_i32_16x16x64_i8 v[52:55], v[140:143], v[176:179], v[52:55]
	v_mfma_i32_16x16x64_i8 v[44:47], v[144:147], v[202:205], v[44:47]
	v_mfma_i32_16x16x64_i8 v[36:39], v[140:143], v[202:205], v[36:39]
	v_mfma_i32_16x16x64_i8 v[28:31], v[144:147], v[210:213], v[28:31]
	v_mfma_i32_16x16x64_i8 v[20:23], v[140:143], v[210:213], v[20:23]
	v_mfma_i32_16x16x64_i8 v[12:15], v[144:147], v[218:221], v[12:15]
	v_mfma_i32_16x16x64_i8 v[4:7], v[140:143], v[218:221], v[4:7]
	s_nop 0
	v_mfma_i32_16x16x64_i8 v[60:63], v[132:135], v[180:183], v[60:63]
	v_mfma_i32_16x16x64_i8 v[52:55], v[136:139], v[180:183], v[52:55]
	v_mfma_i32_16x16x64_i8 v[44:47], v[132:135], v[206:209], v[44:47]
	v_mfma_i32_16x16x64_i8 v[36:39], v[136:139], v[206:209], v[36:39]
	v_mfma_i32_16x16x64_i8 v[28:31], v[132:135], v[214:217], v[28:31]
	v_mfma_i32_16x16x64_i8 v[20:23], v[136:139], v[214:217], v[20:23]
	v_mfma_i32_16x16x64_i8 v[12:15], v[132:135], v[222:225], v[12:15]
	v_mfma_i32_16x16x64_i8 v[4:7], v[136:139], v[222:225], v[4:7]
	s_nop 0
	s_barrier
	s_add_i32 s21, 0, 0x18000
	s_add_i32 s30, 0, 0x1c000
	v_add_u32_e32 v144, s21, v190
	v_add_u32_e32 v160, s30, v190
	ds_read_b128 v[132:135], v144
	ds_read_b128 v[136:139], v144 offset:1024
	ds_read_b128 v[140:143], v144 offset:2048
	ds_read_b128 v[144:147], v144 offset:3072
	ds_read_b128 v[148:151], v160
	ds_read_b128 v[152:155], v160 offset:1024
	ds_read_b128 v[156:159], v160 offset:2048
	ds_read_b128 v[160:163], v160 offset:3072
	s_add_u32 s24, s66, 0x40000
	s_addc_u32 s25, s67, 0
	s_mov_b32 m0, s56
	v_lshl_add_u64 v[226:227], s[24:25], 0, v[168:169]
	ds_read_b128 v[176:179], v194 offset:32768
	ds_read_b128 v[180:183], v194 offset:33792
	ds_read_b128 v[202:205], v194 offset:34816
	ds_read_b128 v[206:209], v194 offset:35840
	ds_read_b128 v[210:213], v194 offset:36864
	ds_read_b128 v[214:217], v194 offset:37888
	ds_read_b128 v[218:221], v194 offset:38912
	ds_read_b128 v[222:225], v194 offset:39936
	global_load_lds_dwordx4 v[226:227], off
	v_lshl_add_u64 v[226:227], s[24:25], 0, v[166:167]
	s_mov_b32 m0, s70
	s_nop 0
	global_load_lds_dwordx4 v[226:227], off
	s_waitcnt vmcnt(8)
	s_waitcnt lgkmcnt(0)
	s_nop 0
	s_waitcnt lgkmcnt(0)
	v_mfma_i32_16x16x64_i8 v[128:131], v[132:135], v[176:179], v[128:131]
	v_mfma_i32_16x16x64_i8 v[120:123], v[140:143], v[176:179], v[120:123]
	v_mfma_i32_16x16x64_i8 v[112:115], v[132:135], v[202:205], v[112:115]
	v_mfma_i32_16x16x64_i8 v[104:107], v[140:143], v[202:205], v[104:107]
	s_barrier
	v_mfma_i32_16x16x64_i8 v[96:99], v[132:135], v[210:213], v[96:99]
	v_mfma_i32_16x16x64_i8 v[88:91], v[140:143], v[210:213], v[88:91]
	v_mfma_i32_16x16x64_i8 v[80:83], v[132:135], v[218:221], v[80:83]
	v_mfma_i32_16x16x64_i8 v[72:75], v[140:143], v[218:221], v[72:75]
	s_nop 0
	v_mfma_i32_16x16x64_i8 v[128:131], v[136:139], v[180:183], v[128:131]
	v_mfma_i32_16x16x64_i8 v[120:123], v[144:147], v[180:183], v[120:123]
	v_mfma_i32_16x16x64_i8 v[112:115], v[136:139], v[206:209], v[112:115]
	v_mfma_i32_16x16x64_i8 v[104:107], v[144:147], v[206:209], v[104:107]
	v_mfma_i32_16x16x64_i8 v[96:99], v[136:139], v[214:217], v[96:99]
	v_mfma_i32_16x16x64_i8 v[88:91], v[144:147], v[214:217], v[88:91]
	v_mfma_i32_16x16x64_i8 v[80:83], v[136:139], v[222:225], v[80:83]
	v_mfma_i32_16x16x64_i8 v[72:75], v[144:147], v[222:225], v[72:75]
	s_nop 0
	s_nop 0
	v_mfma_i32_16x16x64_i8 v[124:127], v[148:151], v[176:179], v[124:127]
	v_mfma_i32_16x16x64_i8 v[116:119], v[156:159], v[176:179], v[116:119]
	v_mfma_i32_16x16x64_i8 v[108:111], v[148:151], v[202:205], v[108:111]
	v_mfma_i32_16x16x64_i8 v[100:103], v[156:159], v[202:205], v[100:103]
	v_mfma_i32_16x16x64_i8 v[92:95], v[148:151], v[210:213], v[92:95]
	v_mfma_i32_16x16x64_i8 v[84:87], v[156:159], v[210:213], v[84:87]
	v_mfma_i32_16x16x64_i8 v[76:79], v[148:151], v[218:221], v[76:79]
	v_mfma_i32_16x16x64_i8 v[68:71], v[156:159], v[218:221], v[68:71]
	s_nop 0
	v_mfma_i32_16x16x64_i8 v[124:127], v[152:155], v[180:183], v[124:127]
	v_mfma_i32_16x16x64_i8 v[116:119], v[160:163], v[180:183], v[116:119]
	v_mfma_i32_16x16x64_i8 v[108:111], v[152:155], v[206:209], v[108:111]
	v_mfma_i32_16x16x64_i8 v[100:103], v[160:163], v[206:209], v[100:103]
	v_mfma_i32_16x16x64_i8 v[92:95], v[152:155], v[214:217], v[92:95]
	v_mfma_i32_16x16x64_i8 v[84:87], v[160:163], v[214:217], v[84:87]
	v_mfma_i32_16x16x64_i8 v[76:79], v[152:155], v[222:225], v[76:79]
	v_mfma_i32_16x16x64_i8 v[68:71], v[160:163], v[222:225], v[68:71]
	s_nop 0
	s_barrier
; #define G_STAGE(bufoff, gbase, voff) do { _Pragma("unroll") for (int _i = 0; _i < 2; ++_i) \
;         __builtin_amdgcn_global_load_lds((const unsigned*)((const char*)(gbase) + (voff)[_i]), (LAS unsigned*)(lds + (bufoff) + ldsw + _i * 8192), 16, 0, 0); } while (0)
; #define G_LDA(dst, b, h) do { _Pragma("unroll") for (int m = 0; m < 4; ++m) { const i32x4 _p0 = *(const LAS i32x4*)(lds + G_SA(b, h) + aoff + m * 2048), _p1 = *(const LAS i32x4*)(lds + G_SA(b, h) + aoff + m * 2048 + 1024); \
;         dst[m] = __builtin_shufflevector(_p0, _p1, 0, 1, 2, 3, 4, 5, 6, 7); } } while (0)
; #define G_WAIT_V(n) asm volatile("s_waitcnt vmcnt(" #n ")" ::: "memory")
; #define G_WAIT_L(n) asm volatile("s_waitcnt lgkmcnt(" #n ")" ::: "memory")
; #define G_BAR __builtin_amdgcn_s_barrier()
; #define G_SCHED __builtin_amdgcn_sched_barrier(0)
; template <int NS, int MODE  , class Epi>
; __device__ __forceinline__ void gemm_phase(LAS unsigned char* lds, const Gemm g, const StaticOrder& S, const Epi& E) {
;     ...
;         for (int t = 0; t < NT; t += 2) {
;     ...
;             G_LDA(At, 1, 1); G_STAGE(G_SB(1, 0), b3, voffB); G_STAGE(G_SB(1, 1), b3 + hstep, voffB); G_STAGE(G_SA(1, 0), a3, voffA);
;             G_WAIT_V(8); G_WAIT_L(0); G_BAR; G_MMA(1, 0, At, B0); G_MMA(1, 1, At, B1); G_BAR; G_SCHED;
	s_add_i32 s21, s21, s18
	v_lshl_add_u64 v[226:227], s[64:65], 0, v[2:3]
	s_mov_b32 m0, s21
	ds_read_b128 v[176:179], v194 offset:49152
	ds_read_b128 v[180:183], v194 offset:50176
	ds_read_b128 v[202:205], v194 offset:51200
	ds_read_b128 v[206:209], v194 offset:52224
	ds_read_b128 v[210:213], v194 offset:53248
	ds_read_b128 v[214:217], v194 offset:54272
	ds_read_b128 v[218:221], v194 offset:55296
	ds_read_b128 v[222:225], v194 offset:56320
	global_load_lds_dwordx4 v[226:227], off
	s_add_i32 m0, s21, 0x2000
	s_add_u32 s24, s64, 0x40000
	v_lshl_add_u64 v[226:227], s[64:65], 0, v[164:165]
	s_addc_u32 s25, s65, 0
	s_add_i32 s21, s30, s18
	global_load_lds_dwordx4 v[226:227], off
	v_lshl_add_u64 v[226:227], s[24:25], 0, v[2:3]
	s_mov_b32 m0, s21
	s_nop 0
	global_load_lds_dwordx4 v[226:227], off
	v_lshl_add_u64 v[226:227], s[24:25], 0, v[164:165]
	s_add_i32 m0, s21, 0x2000
	s_nop 0
	global_load_lds_dwordx4 v[226:227], off
	v_lshl_add_u64 v[226:227], s[62:63], 0, v[168:169]
	s_mov_b32 m0, s71
	s_nop 0
	global_load_lds_dwordx4 v[226:227], off
	v_lshl_add_u64 v[226:227], s[62:63], 0, v[166:167]
	s_mov_b32 m0, s72
	s_nop 0
	global_load_lds_dwordx4 v[226:227], off
	s_waitcnt vmcnt(8)
	s_waitcnt lgkmcnt(0)
	s_nop 0
	s_waitcnt lgkmcnt(0)
	v_mfma_i32_16x16x64_i8 v[64:67], v[132:135], v[176:179], v[64:67]
	v_mfma_i32_16x16x64_i8 v[56:59], v[140:143], v[176:179], v[56:59]
	v_mfma_i32_16x16x64_i8 v[48:51], v[132:135], v[202:205], v[48:51]
	v_mfma_i32_16x16x64_i8 v[40:43], v[140:143], v[202:205], v[40:43]
	s_barrier
	v_mfma_i32_16x16x64_i8 v[32:35], v[132:135], v[210:213], v[32:35]
	v_mfma_i32_16x16x64_i8 v[24:27], v[140:143], v[210:213], v[24:27]
	v_mfma_i32_16x16x64_i8 v[16:19], v[132:135], v[218:221], v[16:19]
	v_mfma_i32_16x16x64_i8 v[8:11], v[140:143], v[218:221], v[8:11]
	s_nop 0
	v_mfma_i32_16x16x64_i8 v[64:67], v[136:139], v[180:183], v[64:67]
	v_mfma_i32_16x16x64_i8 v[56:59], v[144:147], v[180:183], v[56:59]
	v_mfma_i32_16x16x64_i8 v[48:51], v[136:139], v[206:209], v[48:51]
	v_mfma_i32_16x16x64_i8 v[40:43], v[144:147], v[206:209], v[40:43]
	v_mfma_i32_16x16x64_i8 v[32:35], v[136:139], v[214:217], v[32:35]
	v_mfma_i32_16x16x64_i8 v[24:27], v[144:147], v[214:217], v[24:27]
	v_mfma_i32_16x16x64_i8 v[16:19], v[136:139], v[222:225], v[16:19]
	v_mfma_i32_16x16x64_i8 v[8:11], v[144:147], v[222:225], v[8:11]
	s_nop 0
	s_nop 0
	v_mfma_i32_16x16x64_i8 v[60:63], v[148:151], v[176:179], v[60:63]
	v_mfma_i32_16x16x64_i8 v[52:55], v[156:159], v[176:179], v[52:55]
	v_mfma_i32_16x16x64_i8 v[44:47], v[148:151], v[202:205], v[44:47]
	v_mfma_i32_16x16x64_i8 v[36:39], v[156:159], v[202:205], v[36:39]
	v_mfma_i32_16x16x64_i8 v[28:31], v[148:151], v[210:213], v[28:31]
	v_mfma_i32_16x16x64_i8 v[20:23], v[156:159], v[210:213], v[20:23]
	v_mfma_i32_16x16x64_i8 v[12:15], v[148:151], v[218:221], v[12:15]
	v_mfma_i32_16x16x64_i8 v[4:7], v[156:159], v[218:221], v[4:7]
	s_nop 0
	v_mfma_i32_16x16x64_i8 v[60:63], v[152:155], v[180:183], v[60:63]
	v_mfma_i32_16x16x64_i8 v[52:55], v[160:163], v[180:183], v[52:55]
	v_mfma_i32_16x16x64_i8 v[44:47], v[152:155], v[206:209], v[44:47]
	v_mfma_i32_16x16x64_i8 v[36:39], v[160:163], v[206:209], v[36:39]
	v_mfma_i32_16x16x64_i8 v[28:31], v[152:155], v[214:217], v[28:31]
	v_mfma_i32_16x16x64_i8 v[20:23], v[160:163], v[214:217], v[20:23]
	v_mfma_i32_16x16x64_i8 v[12:15], v[152:155], v[222:225], v[12:15]
	v_mfma_i32_16x16x64_i8 v[4:7], v[160:163], v[222:225], v[4:7]
	s_nop 0
	s_barrier
	s_add_i32 s13, s13, 2
	s_add_u32 s60, s60, 0x100
	s_addc_u32 s61, s61, 0
	s_cmp_gt_u32 s13, 13
	s_cbranch_scc1 .LBB0_1279

; #define G_STAGE(bufoff, gbase, voff) do { _Pragma("unroll") for (int _i = 0; _i < 2; ++_i) \
;         __builtin_amdgcn_global_load_lds((const unsigned*)((const char*)(gbase) + (voff)[_i]), (LAS unsigned*)(lds + (bufoff) + ldsw + _i * 8192), 16, 0, 0); } while (0)
; #define G_LDA(dst, b, h) do { _Pragma("unroll") for (int m = 0; m < 4; ++m) { const i32x4 _p0 = *(const LAS i32x4*)(lds + G_SA(b, h) + aoff + m * 2048), _p1 = *(const LAS i32x4*)(lds + G_SA(b, h) + aoff + m * 2048 + 1024); \
;         dst[m] = __builtin_shufflevector(_p0, _p1, 0, 1, 2, 3, 4, 5, 6, 7); } } while (0)
; #define G_LDB(dst, b, h) do { _Pragma("unroll") for (int n = 0; n < 2; ++n) { const i32x4 _p0 = *(const LAS i32x4*)(lds + G_SB(b, h) + boff + n * 2048), _p1 = *(const LAS i32x4*)(lds + G_SB(b, h) + boff + n * 2048 + 1024); \
;         dst[n] = __builtin_shufflevector(_p0, _p1, 0, 1, 2, 3, 4, 5, 6, 7); } } while (0)
; #define G_WAIT_V(n) asm volatile("s_waitcnt vmcnt(" #n ")" ::: "memory")
; #define G_WAIT_L(n) asm volatile("s_waitcnt lgkmcnt(" #n ")" ::: "memory")
; #define G_BAR __builtin_amdgcn_s_barrier()
; #define G_SCHED __builtin_amdgcn_sched_barrier(0)
; template <int NS, int MODE  , class Epi>
; __device__ __forceinline__ void gemm_phase(LAS unsigned char* lds, const Gemm g, const StaticOrder& S, const Epi& E) {
;     ...
;             G_LDB(B0, 0, 0); G_LDB(B1, 0, 1); G_SCHED; G_LDA(At, 0, 0); G_STAGE(G_SA(1, 1), a1 + hstep, voffA);
;             G_WAIT_V(8); G_WAIT_L(0); G_BAR; G_MMA(0, 0, At, B0); G_MMA(0, 1, At, B1); G_BAR; G_SCHED;
;             G_LDA(At, 0, 1); G_STAGE(G_SB(0, 0), b2, voffB); G_STAGE(G_SB(0, 1), b2 + hstep, voffB); G_STAGE(G_SA(0, 0), a2, voffA);
;             G_WAIT_V(8); G_WAIT_L(0); G_BAR; G_MMA(1, 0, At, B0); G_MMA(1, 1, At, B1); G_BAR; G_SCHED;
;             G_LDB(B0, 1, 0); G_LDB(B1, 1, 1); G_SCHED; G_LDA(At, 1, 0); G_STAGE(G_SA(0, 1), a2 + hstep, voffA);
;             G_WAIT_V(8); G_WAIT_L(0); G_BAR; G_MMA(0, 0, At, B0); G_MMA(0, 1, At, B1); G_BAR; G_SCHED;
.LBB0_1357:
	s_add_i32 s25, 0, 0x10000
	s_add_i32 s30, 0, 0x14000
	v_add_u32_e32 v4, s25, v214
	v_add_u32_e32 v16, s30, v214
	ds_read_b128 v[20:23], v4
	ds_read_b128 v[24:27], v4 offset:1024
	ds_read_b128 v[28:31], v4 offset:2048
	ds_read_b128 v[32:35], v4 offset:3072
	ds_read_b128 v[4:7], v16
	ds_read_b128 v[8:11], v16 offset:1024
	ds_read_b128 v[12:15], v16 offset:2048
	ds_read_b128 v[16:19], v16 offset:3072
	v_lshl_add_u64 v[176:177], v[164:165], 0, s[48:49]
	s_add_i32 m0, s19, 0xc000
	ds_read_b128 v[188:191], v216
	ds_read_b128 v[192:195], v216 offset:1024
	ds_read_b128 v[196:199], v216 offset:2048
	ds_read_b128 v[200:203], v216 offset:3072
	ds_read_b128 v[204:207], v216 offset:4096
	ds_read_b128 v[208:211], v216 offset:5120
	ds_read_b128 v[218:221], v216 offset:6144
	ds_read_b128 v[222:225], v216 offset:7168
	global_load_lds_dwordx4 v[176:177], off
	v_lshl_add_u64 v[176:177], v[166:167], 0, s[48:49]
	s_add_i32 m0, s19, 0xe000
	s_nop 0
	global_load_lds_dwordx4 v[176:177], off
	s_waitcnt vmcnt(8)
	s_waitcnt lgkmcnt(0)
	s_nop 0
	s_waitcnt lgkmcnt(0)
	v_mfma_scale_f32_16x16x128_f8f6f4 v[160:163], v[20:27], v[188:195], v[160:163], v212, v212 op_sel_hi:[0,0,0]
	v_mfma_scale_f32_16x16x128_f8f6f4 v[156:159], v[28:35], v[188:195], v[156:159], v212, v212 op_sel_hi:[0,0,0]
	v_mfma_scale_f32_16x16x128_f8f6f4 v[144:147], v[20:27], v[196:203], v[144:147], v212, v212 op_sel_hi:[0,0,0]
	v_mfma_scale_f32_16x16x128_f8f6f4 v[140:143], v[28:35], v[196:203], v[140:143], v212, v212 op_sel_hi:[0,0,0]
	s_barrier
	v_mfma_scale_f32_16x16x128_f8f6f4 v[128:131], v[20:27], v[204:211], v[128:131], v212, v212 op_sel_hi:[0,0,0]
	v_mfma_scale_f32_16x16x128_f8f6f4 v[124:127], v[28:35], v[204:211], v[124:127], v212, v212 op_sel_hi:[0,0,0]
	v_mfma_scale_f32_16x16x128_f8f6f4 v[112:115], v[20:27], v[218:225], v[112:115], v212, v212 op_sel_hi:[0,0,0]
	v_mfma_scale_f32_16x16x128_f8f6f4 v[108:111], v[28:35], v[218:225], v[108:111], v212, v212 op_sel_hi:[0,0,0]
	s_nop 0
	s_nop 0
	v_mfma_scale_f32_16x16x128_f8f6f4 v[152:155], v[4:11], v[188:195], v[152:155], v212, v212 op_sel_hi:[0,0,0]
	v_mfma_scale_f32_16x16x128_f8f6f4 v[148:151], v[12:19], v[188:195], v[148:151], v212, v212 op_sel_hi:[0,0,0]
	v_mfma_scale_f32_16x16x128_f8f6f4 v[136:139], v[4:11], v[196:203], v[136:139], v212, v212 op_sel_hi:[0,0,0]
	v_mfma_scale_f32_16x16x128_f8f6f4 v[132:135], v[12:19], v[196:203], v[132:135], v212, v212 op_sel_hi:[0,0,0]
	v_mfma_scale_f32_16x16x128_f8f6f4 v[120:123], v[4:11], v[204:211], v[120:123], v212, v212 op_sel_hi:[0,0,0]
	v_mfma_scale_f32_16x16x128_f8f6f4 v[116:119], v[12:19], v[204:211], v[116:119], v212, v212 op_sel_hi:[0,0,0]
	v_mfma_scale_f32_16x16x128_f8f6f4 v[104:107], v[4:11], v[218:225], v[104:107], v212, v212 op_sel_hi:[0,0,0]
	v_mfma_scale_f32_16x16x128_f8f6f4 v[100:103], v[12:19], v[218:225], v[100:103], v212, v212 op_sel_hi:[0,0,0]
	s_nop 0
	s_barrier
	s_add_i32 s25, s25, s18
	v_lshl_add_u64 v[176:177], s[60:61], 0, v[2:3]
	s_mov_b32 m0, s25
	ds_read_b128 v[188:191], v216 offset:16384
	ds_read_b128 v[192:195], v216 offset:17408
	ds_read_b128 v[196:199], v216 offset:18432
	ds_read_b128 v[200:203], v216 offset:19456
	ds_read_b128 v[204:207], v216 offset:20480
	ds_read_b128 v[208:211], v216 offset:21504
	ds_read_b128 v[218:221], v216 offset:22528
	ds_read_b128 v[222:225], v216 offset:23552
	global_load_lds_dwordx4 v[176:177], off
	s_add_i32 m0, s25, 0x2000
	v_lshl_add_u64 v[176:177], s[60:61], 0, v[172:173]
	s_add_u32 s60, s60, 0xb0000
	s_addc_u32 s61, s61, 0
	s_add_i32 s25, s30, s18
	global_load_lds_dwordx4 v[176:177], off
	v_lshl_add_u64 v[176:177], s[60:61], 0, v[2:3]
	s_mov_b32 m0, s25
	s_nop 0
	global_load_lds_dwordx4 v[176:177], off
	v_lshl_add_u64 v[176:177], s[60:61], 0, v[172:173]
	s_add_i32 m0, s25, 0x2000
	s_nop 0
	global_load_lds_dwordx4 v[176:177], off
	v_lshl_add_u64 v[176:177], s[58:59], 0, v[168:169]
	s_mov_b32 m0, s19
	s_nop 0
	global_load_lds_dwordx4 v[176:177], off
	v_lshl_add_u64 v[176:177], s[58:59], 0, v[170:171]
	s_mov_b32 m0, s29
	s_nop 0
	global_load_lds_dwordx4 v[176:177], off
	s_waitcnt vmcnt(8)
	s_waitcnt lgkmcnt(0)
	s_nop 0
	s_waitcnt lgkmcnt(0)
	v_mfma_scale_f32_16x16x128_f8f6f4 v[96:99], v[20:27], v[188:195], v[96:99], v212, v212 op_sel_hi:[0,0,0]
	v_mfma_scale_f32_16x16x128_f8f6f4 v[92:95], v[28:35], v[188:195], v[92:95], v212, v212 op_sel_hi:[0,0,0]
	v_mfma_scale_f32_16x16x128_f8f6f4 v[80:83], v[20:27], v[196:203], v[80:83], v212, v212 op_sel_hi:[0,0,0]
	v_mfma_scale_f32_16x16x128_f8f6f4 v[76:79], v[28:35], v[196:203], v[76:79], v212, v212 op_sel_hi:[0,0,0]
	s_barrier
	v_mfma_scale_f32_16x16x128_f8f6f4 v[64:67], v[20:27], v[204:211], v[64:67], v212, v212 op_sel_hi:[0,0,0]
	v_mfma_scale_f32_16x16x128_f8f6f4 v[60:63], v[28:35], v[204:211], v[60:63], v212, v212 op_sel_hi:[0,0,0]
	v_mfma_scale_f32_16x16x128_f8f6f4 v[48:51], v[20:27], v[218:225], v[48:51], v212, v212 op_sel_hi:[0,0,0]
	v_mfma_scale_f32_16x16x128_f8f6f4 v[44:47], v[28:35], v[218:225], v[44:47], v212, v212 op_sel_hi:[0,0,0]
	s_nop 0
	s_nop 0
	v_mfma_scale_f32_16x16x128_f8f6f4 v[88:91], v[4:11], v[188:195], v[88:91], v212, v212 op_sel_hi:[0,0,0]
	v_mfma_scale_f32_16x16x128_f8f6f4 v[84:87], v[12:19], v[188:195], v[84:87], v212, v212 op_sel_hi:[0,0,0]
	v_mfma_scale_f32_16x16x128_f8f6f4 v[72:75], v[4:11], v[196:203], v[72:75], v212, v212 op_sel_hi:[0,0,0]
	v_mfma_scale_f32_16x16x128_f8f6f4 v[68:71], v[12:19], v[196:203], v[68:71], v212, v212 op_sel_hi:[0,0,0]
	v_mfma_scale_f32_16x16x128_f8f6f4 v[56:59], v[4:11], v[204:211], v[56:59], v212, v212 op_sel_hi:[0,0,0]
	v_mfma_scale_f32_16x16x128_f8f6f4 v[52:55], v[12:19], v[204:211], v[52:55], v212, v212 op_sel_hi:[0,0,0]
	v_mfma_scale_f32_16x16x128_f8f6f4 v[40:43], v[4:11], v[218:225], v[40:43], v212, v212 op_sel_hi:[0,0,0]
	v_mfma_scale_f32_16x16x128_f8f6f4 v[36:39], v[12:19], v[218:225], v[36:39], v212, v212 op_sel_hi:[0,0,0]
	s_nop 0
	s_barrier
; #define G_STAGE(bufoff, gbase, voff) do { _Pragma("unroll") for (int _i = 0; _i < 2; ++_i) \
;         __builtin_amdgcn_global_load_lds((const unsigned*)((const char*)(gbase) + (voff)[_i]), (LAS unsigned*)(lds + (bufoff) + ldsw + _i * 8192), 16, 0, 0); } while (0)
; #define G_LDA(dst, b, h) do { _Pragma("unroll") for (int m = 0; m < 4; ++m) { const i32x4 _p0 = *(const LAS i32x4*)(lds + G_SA(b, h) + aoff + m * 2048), _p1 = *(const LAS i32x4*)(lds + G_SA(b, h) + aoff + m * 2048 + 1024); \
;         dst[m] = __builtin_shufflevector(_p0, _p1, 0, 1, 2, 3, 4, 5, 6, 7); } } while (0)
; #define G_LDB(dst, b, h) do { _Pragma("unroll") for (int n = 0; n < 2; ++n) { const i32x4 _p0 = *(const LAS i32x4*)(lds + G_SB(b, h) + boff + n * 2048), _p1 = *(const LAS i32x4*)(lds + G_SB(b, h) + boff + n * 2048 + 1024); \
;         dst[n] = __builtin_shufflevector(_p0, _p1, 0, 1, 2, 3, 4, 5, 6, 7); } } while (0)
; #define G_WAIT_V(n) asm volatile("s_waitcnt vmcnt(" #n ")" ::: "memory")
; #define G_WAIT_L(n) asm volatile("s_waitcnt lgkmcnt(" #n ")" ::: "memory")
; #define G_BAR __builtin_amdgcn_s_barrier()
; #define G_SCHED __builtin_amdgcn_sched_barrier(0)
; template <int NS, int MODE  , class Epi>
; __device__ __forceinline__ void gemm_phase(LAS unsigned char* lds, const Gemm g, const StaticOrder& S, const Epi& E) {
;     ...
;             G_LDB(B0, 1, 0); G_LDB(B1, 1, 1); G_SCHED; G_LDA(At, 1, 0); G_STAGE(G_SA(0, 1), a2 + hstep, voffA);
;             G_WAIT_V(8); G_WAIT_L(0); G_BAR; G_MMA(0, 0, At, B0); G_MMA(0, 1, At, B1); G_BAR; G_SCHED;
;             G_LDA(At, 1, 1); G_STAGE(G_SB(1, 0), b3, voffB); G_STAGE(G_SB(1, 1), b3 + hstep, voffB); G_STAGE(G_SA(1, 0), a3, voffA);
;             G_WAIT_V(8); G_WAIT_L(0); G_BAR; G_MMA(1, 0, At, B0); G_MMA(1, 1, At, B1); G_BAR; G_SCHED;
	s_add_i32 s25, 0, 0x18000
	s_add_i32 s35, 0, 0x1c000
	v_add_u32_e32 v16, s25, v214
	v_add_u32_e32 v32, s35, v214
	ds_read_b128 v[4:7], v16
	ds_read_b128 v[8:11], v16 offset:1024
	ds_read_b128 v[12:15], v16 offset:2048
	ds_read_b128 v[16:19], v16 offset:3072
	ds_read_b128 v[20:23], v32
	ds_read_b128 v[24:27], v32 offset:1024
	ds_read_b128 v[28:31], v32 offset:2048
	ds_read_b128 v[32:35], v32 offset:3072
	s_add_u32 s30, s58, 0xb0000
	s_addc_u32 s31, s59, 0
	s_mov_b32 m0, s56
	v_lshl_add_u64 v[176:177], s[30:31], 0, v[168:169]
	ds_read_b128 v[188:191], v216 offset:32768
	ds_read_b128 v[192:195], v216 offset:33792
	ds_read_b128 v[196:199], v216 offset:34816
	ds_read_b128 v[200:203], v216 offset:35840
	ds_read_b128 v[204:207], v216 offset:36864
	ds_read_b128 v[208:211], v216 offset:37888
	ds_read_b128 v[218:221], v216 offset:38912
	ds_read_b128 v[222:225], v216 offset:39936
	global_load_lds_dwordx4 v[176:177], off
	v_lshl_add_u64 v[176:177], s[30:31], 0, v[170:171]
	s_mov_b32 m0, s62
	s_nop 0
	global_load_lds_dwordx4 v[176:177], off
	s_waitcnt vmcnt(8)
	s_waitcnt lgkmcnt(0)
	s_nop 0
	s_waitcnt lgkmcnt(0)
	v_mfma_scale_f32_16x16x128_f8f6f4 v[160:163], v[4:11], v[188:195], v[160:163], v212, v212 op_sel_hi:[0,0,0]
	v_mfma_scale_f32_16x16x128_f8f6f4 v[156:159], v[12:19], v[188:195], v[156:159], v212, v212 op_sel_hi:[0,0,0]
	v_mfma_scale_f32_16x16x128_f8f6f4 v[144:147], v[4:11], v[196:203], v[144:147], v212, v212 op_sel_hi:[0,0,0]
	v_mfma_scale_f32_16x16x128_f8f6f4 v[140:143], v[12:19], v[196:203], v[140:143], v212, v212 op_sel_hi:[0,0,0]
	s_barrier
	v_mfma_scale_f32_16x16x128_f8f6f4 v[128:131], v[4:11], v[204:211], v[128:131], v212, v212 op_sel_hi:[0,0,0]
	v_mfma_scale_f32_16x16x128_f8f6f4 v[124:127], v[12:19], v[204:211], v[124:127], v212, v212 op_sel_hi:[0,0,0]
	v_mfma_scale_f32_16x16x128_f8f6f4 v[112:115], v[4:11], v[218:225], v[112:115], v212, v212 op_sel_hi:[0,0,0]
	v_mfma_scale_f32_16x16x128_f8f6f4 v[108:111], v[12:19], v[218:225], v[108:111], v212, v212 op_sel_hi:[0,0,0]
	s_nop 0
	s_nop 0
	v_mfma_scale_f32_16x16x128_f8f6f4 v[152:155], v[20:27], v[188:195], v[152:155], v212, v212 op_sel_hi:[0,0,0]
	v_mfma_scale_f32_16x16x128_f8f6f4 v[148:151], v[28:35], v[188:195], v[148:151], v212, v212 op_sel_hi:[0,0,0]
	v_mfma_scale_f32_16x16x128_f8f6f4 v[136:139], v[20:27], v[196:203], v[136:139], v212, v212 op_sel_hi:[0,0,0]
	v_mfma_scale_f32_16x16x128_f8f6f4 v[132:135], v[28:35], v[196:203], v[132:135], v212, v212 op_sel_hi:[0,0,0]
	v_mfma_scale_f32_16x16x128_f8f6f4 v[120:123], v[20:27], v[204:211], v[120:123], v212, v212 op_sel_hi:[0,0,0]
	v_mfma_scale_f32_16x16x128_f8f6f4 v[116:119], v[28:35], v[204:211], v[116:119], v212, v212 op_sel_hi:[0,0,0]
	v_mfma_scale_f32_16x16x128_f8f6f4 v[104:107], v[20:27], v[218:225], v[104:107], v212, v212 op_sel_hi:[0,0,0]
	v_mfma_scale_f32_16x16x128_f8f6f4 v[100:103], v[28:35], v[218:225], v[100:103], v212, v212 op_sel_hi:[0,0,0]
	s_nop 0
	s_barrier
	s_add_i32 s25, s25, s18
	v_lshl_add_u64 v[176:177], s[54:55], 0, v[2:3]
	s_mov_b32 m0, s25
	ds_read_b128 v[188:191], v216 offset:49152
	ds_read_b128 v[192:195], v216 offset:50176
	ds_read_b128 v[196:199], v216 offset:51200
	ds_read_b128 v[200:203], v216 offset:52224
	ds_read_b128 v[204:207], v216 offset:53248
	ds_read_b128 v[208:211], v216 offset:54272
	ds_read_b128 v[218:221], v216 offset:55296
	ds_read_b128 v[222:225], v216 offset:56320
	global_load_lds_dwordx4 v[176:177], off
	s_add_i32 m0, s25, 0x2000
	s_add_u32 s30, s54, 0xb0000
	v_lshl_add_u64 v[176:177], s[54:55], 0, v[172:173]
	s_addc_u32 s31, s55, 0
	s_add_i32 s25, s35, s18
	global_load_lds_dwordx4 v[176:177], off
	v_lshl_add_u64 v[176:177], s[30:31], 0, v[2:3]
	s_mov_b32 m0, s25
	s_nop 0
	global_load_lds_dwordx4 v[176:177], off
	v_lshl_add_u64 v[176:177], s[30:31], 0, v[172:173]
	s_add_i32 m0, s25, 0x2000
	s_nop 0
	global_load_lds_dwordx4 v[176:177], off
	v_lshl_add_u64 v[176:177], s[52:53], 0, v[168:169]
	s_mov_b32 m0, s65
	s_nop 0
	global_load_lds_dwordx4 v[176:177], off
	v_lshl_add_u64 v[176:177], s[52:53], 0, v[170:171]
	s_mov_b32 m0, s66
	s_nop 0
	global_load_lds_dwordx4 v[176:177], off
	s_waitcnt vmcnt(8)
	s_waitcnt lgkmcnt(0)
	s_nop 0
	s_waitcnt lgkmcnt(0)
	v_mfma_scale_f32_16x16x128_f8f6f4 v[96:99], v[4:11], v[188:195], v[96:99], v212, v212 op_sel_hi:[0,0,0]
	v_mfma_scale_f32_16x16x128_f8f6f4 v[92:95], v[12:19], v[188:195], v[92:95], v212, v212 op_sel_hi:[0,0,0]
	v_mfma_scale_f32_16x16x128_f8f6f4 v[80:83], v[4:11], v[196:203], v[80:83], v212, v212 op_sel_hi:[0,0,0]
	v_mfma_scale_f32_16x16x128_f8f6f4 v[76:79], v[12:19], v[196:203], v[76:79], v212, v212 op_sel_hi:[0,0,0]
	s_barrier
	v_mfma_scale_f32_16x16x128_f8f6f4 v[64:67], v[4:11], v[204:211], v[64:67], v212, v212 op_sel_hi:[0,0,0]
	v_mfma_scale_f32_16x16x128_f8f6f4 v[60:63], v[12:19], v[204:211], v[60:63], v212, v212 op_sel_hi:[0,0,0]
	v_mfma_scale_f32_16x16x128_f8f6f4 v[48:51], v[4:11], v[218:225], v[48:51], v212, v212 op_sel_hi:[0,0,0]
	v_mfma_scale_f32_16x16x128_f8f6f4 v[44:47], v[12:19], v[218:225], v[44:47], v212, v212 op_sel_hi:[0,0,0]
	s_nop 0
	s_nop 0
	v_mfma_scale_f32_16x16x128_f8f6f4 v[88:91], v[20:27], v[188:195], v[88:91], v212, v212 op_sel_hi:[0,0,0]
	v_mfma_scale_f32_16x16x128_f8f6f4 v[84:87], v[28:35], v[188:195], v[84:87], v212, v212 op_sel_hi:[0,0,0]
	v_mfma_scale_f32_16x16x128_f8f6f4 v[72:75], v[20:27], v[196:203], v[72:75], v212, v212 op_sel_hi:[0,0,0]
	v_mfma_scale_f32_16x16x128_f8f6f4 v[68:71], v[28:35], v[196:203], v[68:71], v212, v212 op_sel_hi:[0,0,0]
	v_mfma_scale_f32_16x16x128_f8f6f4 v[56:59], v[20:27], v[204:211], v[56:59], v212, v212 op_sel_hi:[0,0,0]
	v_mfma_scale_f32_16x16x128_f8f6f4 v[52:55], v[28:35], v[204:211], v[52:55], v212, v212 op_sel_hi:[0,0,0]
	v_mfma_scale_f32_16x16x128_f8f6f4 v[40:43], v[20:27], v[218:225], v[40:43], v212, v212 op_sel_hi:[0,0,0]
	v_mfma_scale_f32_16x16x128_f8f6f4 v[36:39], v[28:35], v[218:225], v[36:39], v212, v212 op_sel_hi:[0,0,0]
	s_nop 0
	s_barrier
	s_add_i32 s24, s24, 2
	s_add_u32 s48, s48, 0x100
	s_addc_u32 s49, s49, 0
	s_cmp_gt_u32 s24, 41
	s_cbranch_scc1 .LBB0_1360
